# P1 epilogue transposed stores now software-pipelined: each site's wait+store is deferred to the next site of the same class (separate temp quads / SGPR bases per class)
# speedup vs baseline: 1.0093x; 1.0093x over previous
; __device__ __forceinline__ unsigned cvt_pk_bf16(float lo, float hi) { unsigned r; asm volatile("v_cvt_pk_bf16_f32 %0, %1, %2" : "=v"(r) : "v"(lo), "v"(hi)); return r; }
; __device__ __forceinline__ float quad_sum(float s) { s += __shfl_xor(s, 16); s += __shfl_xor(s, 32); return s; }
;     __device__ __forceinline__ void operator()(const f32x4 (&acc)[2][2][4][2], const Unit& u, int wr, int wc, int fr, int fq) const {
;     ...
;             const int sec = pn >> 1, head = 4 * (pn & 1) + wc; const bool prompt = u.pm < (XM_PROMPT / BM);
;             bf16_t* dst = (bf16_t*)(ws + ((sec == 2) ? EW_Q : (sec == 3) ? EW_K : EW_V)); const float* gp = (sec == 2) ? gq : gk;
;             float* fo = (sec == 2) ? nullptr : out + ((sec == 3) ? (prompt ? EO_KP : EO_KS) : (prompt ? EO_VP : EO_VS));
;     ...
;                 for (int m = 0; m < 4; ++m) { const int row = row0 + ai * HALF + m * 16; const int orow = prompt ? row : row - XM_PROMPT;
;                     float ss = 0.f;
; #pragma unroll
;                     for (int bj = 0; bj < 2; ++bj)
; #pragma unroll
;                         for (int n = 0; n < 2; ++n) { const f32x4 x = acc[ai][bj][m][n]; ss += (x[0] * x[0] + x[1] * x[1]) + (x[2] * x[2] + x[3] * x[3]); }
;                     ss = quad_sum(ss);
;                     const float rr = (sec < 4) ? post * (1.0f / sqrtf(ss * (1.0f / 64.0f) + 1e-6f)) : 1.0f;
; #pragma unroll
;                     for (int bj = 0; bj < 2; ++bj) { const f32x4 v0 = acc[ai][bj][m][0] * rr * gv[bj][0], v1 = acc[ai][bj][m][1] * rr * gv[bj][1];
;                         const int dcol = 64 * head + 32 * bj + 8 * fq;
;                         u32x4 w; w.x = cvt_pk_bf16(v0[0], v0[1]); w.y = cvt_pk_bf16(v0[2], v0[3]); w.z = cvt_pk_bf16(v1[0], v1[1]); w.w = cvt_pk_bf16(v1[2], v1[3]);
;                         *(u32x4*)(dst + (size_t)row * 512 + dcol) = w;
;                         if (fo) { float* op = fo + (size_t)orow * 512 + dcol; if (prompt) { __builtin_nontemporal_store(v0, (f32x4*)op); __builtin_nontemporal_store(v1, (f32x4*)(op + 4)); } else { *(f32x4*)op = v0; *(f32x4*)(op + 4) = v1; } } } }
.LBB0_167:
	s_lshl_b32 s10, s88, 2
	s_and_b32 s38, s10, 4
	s_cmp_eq_u32 s13, 3
	s_cselect_b64 s[36:37], -1, 0
	s_and_b64 s[10:11], s[36:37], exec
	s_mov_b32 s10, 0x7500000
	s_cselect_b32 s13, s10, 0x8600000
	s_and_b64 s[10:11], s[8:9], exec
	s_cselect_b32 s39, 0x6400000, s13
	s_cmp_lt_i32 s12, 64
	s_cselect_b64 s[10:11], -1, 0
	s_and_b64 s[12:13], s[10:11], exec
	s_mov_b32 s12, 0x1880000
	s_cselect_b32 s40, s12, 0x20c0000
	s_mov_b32 s12, 0x1080000
	s_cselect_b32 s41, s12, 0x2080000
	s_and_b64 s[12:13], s[36:37], exec
	s_cselect_b32 s12, s41, s40
	v_readlane_b32 s40, v251, 6
	s_lshl_b32 s12, s12, 2
	v_readlane_b32 s46, v251, 12
	v_readlane_b32 s41, v251, 7
	v_readlane_b32 s47, v251, 13
	s_add_u32 s12, s46, s12
	s_addc_u32 s13, s47, 0
	s_or_b32 s36, s38, s75
	v_readlane_b32 s40, v251, 4
	v_add_u32_e32 v146, 0xffffc000, v166
	v_readlane_b32 s41, v251, 5
	s_add_u32 s90, s40, s39
	v_cndmask_b32_e64 v146, v146, v166, s[10:11]
	s_addc_u32 s91, s41, 0
	s_and_b64 s[8:9], s[8:9], exec
	s_waitcnt lgkmcnt(0)
	v_ashrrev_i32_e32 v147, 31, v146
	s_cselect_b32 s13, 0, s13
	s_cselect_b32 s12, 0, s12
	v_lshl_or_b32 v171, s36, 6, v158
	v_ashrrev_i32_e32 v167, 31, v166
	v_lshlrev_b64 v[146:147], 11, v[146:147]
	v_lshlrev_b64 v[148:149], 10, v[166:167]
	v_lshl_add_u64 v[172:173], s[12:13], 0, v[146:147]
	v_pk_mul_f32 v[146:147], v[128:129], v[170:171] op_sel_hi:[1,0]
	v_pk_mul_f32 v[150:151], v[126:127], v[170:171] op_sel_hi:[1,0]
	v_lshl_add_u64 v[168:169], s[90:91], 0, v[148:149]
	s_waitcnt vmcnt(0)
	v_pk_mul_f32 v[148:149], v[144:145], v[146:147]
	v_pk_mul_f32 v[146:147], v[142:143], v[150:151]
	v_pk_mul_f32 v[150:151], v[124:125], v[170:171] op_sel_hi:[1,0]
	v_pk_mul_f32 v[174:175], v[122:123], v[170:171] op_sel_hi:[1,0]
	v_lshlrev_b32_e32 v156, 1, v171
	v_cndmask_b32_e64 v167, 0, 1, s[14:15]
	v_pk_mul_f32 v[152:153], v[136:137], v[150:151]
	v_pk_mul_f32 v[150:151], v[134:135], v[174:175]
	v_lshl_add_u64 v[174:175], v[168:169], 0, v[156:157]
	v_cmp_ne_u32_e64 s[8:9], 1, v167
	s_andn2_b64 vcc, exec, s[14:15]
	v_lshlrev_b32_e32 v168, 2, v171
	v_readlane_b32 s42, v251, 8
	v_readlane_b32 s43, v251, 9
	v_readlane_b32 s44, v251, 10
	v_readlane_b32 s45, v251, 11
	v_cvt_pk_bf16_f32 v186, v146, v147
	v_cvt_pk_bf16_f32 v187, v148, v149
	v_cvt_pk_bf16_f32 v188, v150, v151
	v_cvt_pk_bf16_f32 v189, v152, v153
	s_nop 0
	v_readfirstlane_b32 s98, v174
	v_readfirstlane_b32 s99, v175
	ds_write_b128 v222, v[186:189]
	ds_read_b128 v[230:233], v223
	s_cbranch_vccnz .LBB0_169
	v_mov_b32_e32 v169, v157
	v_lshl_add_u64 v[186:187], v[172:173], 0, v[168:169]
	s_nop 0
	v_readfirstlane_b32 s100, v186
	v_readfirstlane_b32 s101, v187
	ds_write_b128 v225, v[146:149]
	ds_write_b128 v225, v[150:153] offset:16
	ds_read_b128 v[234:237], v226
	ds_read_b128 v[238:241], v226 offset:1024
.LBB0_169:
	v_mov_b32_e32 v171, v170
	s_nop 0
	v_mov_b32_e32 v150, v170
	v_mov_b32_e32 v151, v170
	v_pk_mul_f32 v[146:147], v[120:121], v[150:151]
	v_pk_mul_f32 v[152:153], v[118:119], v[170:171]
	v_pk_mul_f32 v[150:151], v[116:117], v[150:151]
	v_pk_mul_f32 v[170:171], v[114:115], v[170:171]
	v_pk_mul_f32 v[148:149], v[140:141], v[146:147]
	v_pk_mul_f32 v[146:147], v[138:139], v[152:153]
	v_pk_mul_f32 v[152:153], v[132:133], v[150:151]
	v_pk_mul_f32 v[150:151], v[130:131], v[170:171]
	s_and_b64 vcc, exec, s[8:9]
	v_cvt_pk_bf16_f32 v186, v146, v147
	v_cvt_pk_bf16_f32 v187, v148, v149
	v_cvt_pk_bf16_f32 v188, v150, v151
	v_cvt_pk_bf16_f32 v189, v152, v153
	s_waitcnt lgkmcnt(0)
	global_store_dwordx4 v224, v[230:233], s[98:99]
	s_nop 0
	v_readfirstlane_b32 s98, v174
	v_readfirstlane_b32 s99, v175
	ds_write_b128 v222, v[186:189]
	ds_read_b128 v[230:233], v223
	s_cbranch_vccnz .LBB0_171
	v_mov_b32_e32 v169, v157
	v_lshl_add_u64 v[170:171], v[172:173], 0, v[168:169]
	s_nop 0
	v_readfirstlane_b32 s50, v170
	v_readfirstlane_b32 s51, v171
	ds_write_b128 v225, v[146:149]
	ds_write_b128 v225, v[150:153] offset:16
	ds_read_b128 v[242:245], v226
	ds_read_b128 v[246:249], v226 offset:1024

; __device__ __forceinline__ unsigned cvt_pk_bf16(float lo, float hi) { unsigned r; asm volatile("v_cvt_pk_bf16_f32 %0, %1, %2" : "=v"(r) : "v"(lo), "v"(hi)); return r; }
; __device__ __forceinline__ float quad_sum(float s) { s += __shfl_xor(s, 16); s += __shfl_xor(s, 32); return s; }
;     __device__ __forceinline__ void operator()(const f32x4 (&acc)[2][2][4][2], const Unit& u, int wr, int wc, int fr, int fq) const {
;     ...
;                 for (int m = 0; m < 4; ++m) { const int row = row0 + ai * HALF + m * 16; const int orow = prompt ? row : row - XM_PROMPT;
;                     float ss = 0.f;
; #pragma unroll
;                     for (int bj = 0; bj < 2; ++bj)
; #pragma unroll
;                         for (int n = 0; n < 2; ++n) { const f32x4 x = acc[ai][bj][m][n]; ss += (x[0] * x[0] + x[1] * x[1]) + (x[2] * x[2] + x[3] * x[3]); }
;                     ss = quad_sum(ss);
;                     const float rr = (sec < 4) ? post * (1.0f / sqrtf(ss * (1.0f / 64.0f) + 1e-6f)) : 1.0f;
; #pragma unroll
;                     for (int bj = 0; bj < 2; ++bj) { const f32x4 v0 = acc[ai][bj][m][0] * rr * gv[bj][0], v1 = acc[ai][bj][m][1] * rr * gv[bj][1];
;                         const int dcol = 64 * head + 32 * bj + 8 * fq;
;                         u32x4 w; w.x = cvt_pk_bf16(v0[0], v0[1]); w.y = cvt_pk_bf16(v0[2], v0[3]); w.z = cvt_pk_bf16(v1[0], v1[1]); w.w = cvt_pk_bf16(v1[2], v1[3]);
;                         *(u32x4*)(dst + (size_t)row * 512 + dcol) = w;
;                         if (fo) { float* op = fo + (size_t)orow * 512 + dcol; if (prompt) { __builtin_nontemporal_store(v0, (f32x4*)op); __builtin_nontemporal_store(v1, (f32x4*)(op + 4)); } else { *(f32x4*)op = v0; *(f32x4*)(op + 4) = v1; } } } }
.LBB0_173:
	v_or_b32_e32 v146, 16, v166
	s_waitcnt lgkmcnt(0)
	v_add_u32_e32 v147, 0xffffc010, v166
	v_cndmask_b32_e64 v148, v147, v146, s[10:11]
	v_ashrrev_i32_e32 v147, 31, v146
	v_lshlrev_b64 v[146:147], 10, v[146:147]
	v_ashrrev_i32_e32 v149, 31, v148
	v_lshl_add_u64 v[174:175], s[90:91], 0, v[146:147]
	v_lshlrev_b64 v[146:147], 11, v[148:149]
	v_lshl_add_u64 v[170:171], s[12:13], 0, v[146:147]
	v_pk_mul_f32 v[146:147], v[112:113], v[172:173] op_sel_hi:[1,0]
	v_pk_mul_f32 v[150:151], v[110:111], v[172:173] op_sel_hi:[1,0]
	v_pk_mul_f32 v[148:149], v[144:145], v[146:147]
	v_pk_mul_f32 v[146:147], v[142:143], v[150:151]
	v_pk_mul_f32 v[150:151], v[108:109], v[172:173] op_sel_hi:[1,0]
	v_pk_mul_f32 v[186:187], v[106:107], v[172:173] op_sel_hi:[1,0]
	v_pk_mul_f32 v[152:153], v[136:137], v[150:151]
	v_pk_mul_f32 v[150:151], v[134:135], v[186:187]
	v_lshl_add_u64 v[174:175], v[174:175], 0, v[156:157]
	s_and_b64 vcc, exec, s[8:9]
	v_cvt_pk_bf16_f32 v186, v146, v147
	v_cvt_pk_bf16_f32 v187, v148, v149
	v_cvt_pk_bf16_f32 v188, v150, v151
	v_cvt_pk_bf16_f32 v189, v152, v153
	s_waitcnt lgkmcnt(0)
	global_store_dwordx4 v224, v[230:233], s[98:99] offset:64
	s_nop 0
	v_readfirstlane_b32 s98, v174
	v_readfirstlane_b32 s99, v175
	ds_write_b128 v222, v[186:189]
	ds_read_b128 v[230:233], v223
	s_cbranch_vccnz .LBB0_175
	v_mov_b32_e32 v169, v157
	v_lshl_add_u64 v[186:187], v[170:171], 0, v[168:169]
	s_waitcnt lgkmcnt(0)
	global_store_dwordx4 v227, v[234:237], s[100:101]
	global_store_dwordx4 v228, v[238:241], s[100:101]
	s_nop 0
	v_readfirstlane_b32 s100, v186
	v_readfirstlane_b32 s101, v187
	ds_write_b128 v225, v[146:149]
	ds_write_b128 v225, v[150:153] offset:16
	ds_read_b128 v[234:237], v226
	ds_read_b128 v[238:241], v226 offset:1024
.LBB0_175:
	v_mov_b32_e32 v173, v172
	s_nop 0
	v_mov_b32_e32 v150, v172
	v_mov_b32_e32 v151, v172
	v_pk_mul_f32 v[146:147], v[104:105], v[150:151]
	v_pk_mul_f32 v[152:153], v[102:103], v[172:173]
	v_pk_mul_f32 v[150:151], v[100:101], v[150:151]
	v_pk_mul_f32 v[172:173], v[98:99], v[172:173]
	v_pk_mul_f32 v[148:149], v[140:141], v[146:147]
	v_pk_mul_f32 v[146:147], v[138:139], v[152:153]
	v_pk_mul_f32 v[152:153], v[132:133], v[150:151]
	v_pk_mul_f32 v[150:151], v[130:131], v[172:173]
	s_and_b64 vcc, exec, s[8:9]
	v_cvt_pk_bf16_f32 v186, v146, v147
	v_cvt_pk_bf16_f32 v187, v148, v149
	v_cvt_pk_bf16_f32 v188, v150, v151
	v_cvt_pk_bf16_f32 v189, v152, v153
	s_waitcnt lgkmcnt(0)
	global_store_dwordx4 v224, v[230:233], s[98:99]
	s_nop 0
	v_readfirstlane_b32 s98, v174
	v_readfirstlane_b32 s99, v175
	ds_write_b128 v222, v[186:189]
	ds_read_b128 v[230:233], v223
	s_cbranch_vccnz .LBB0_177
	v_mov_b32_e32 v169, v157
	v_lshl_add_u64 v[170:171], v[170:171], 0, v[168:169]
	s_waitcnt lgkmcnt(0)
	global_store_dwordx4 v227, v[242:245], s[50:51] offset:128
	global_store_dwordx4 v228, v[246:249], s[50:51] offset:128
	s_nop 0
	v_readfirstlane_b32 s50, v170
	v_readfirstlane_b32 s51, v171
	ds_write_b128 v225, v[146:149]
	ds_write_b128 v225, v[150:153] offset:16
	ds_read_b128 v[242:245], v226
	ds_read_b128 v[246:249], v226 offset:1024

; __device__ __forceinline__ unsigned cvt_pk_bf16(float lo, float hi) { unsigned r; asm volatile("v_cvt_pk_bf16_f32 %0, %1, %2" : "=v"(r) : "v"(lo), "v"(hi)); return r; }
; __device__ __forceinline__ float quad_sum(float s) { s += __shfl_xor(s, 16); s += __shfl_xor(s, 32); return s; }
;     __device__ __forceinline__ void operator()(const f32x4 (&acc)[2][2][4][2], const Unit& u, int wr, int wc, int fr, int fq) const {
;     ...
;                 for (int m = 0; m < 4; ++m) { const int row = row0 + ai * HALF + m * 16; const int orow = prompt ? row : row - XM_PROMPT;
;                     float ss = 0.f;
; #pragma unroll
;                     for (int bj = 0; bj < 2; ++bj)
; #pragma unroll
;                         for (int n = 0; n < 2; ++n) { const f32x4 x = acc[ai][bj][m][n]; ss += (x[0] * x[0] + x[1] * x[1]) + (x[2] * x[2] + x[3] * x[3]); }
;                     ss = quad_sum(ss);
;                     const float rr = (sec < 4) ? post * (1.0f / sqrtf(ss * (1.0f / 64.0f) + 1e-6f)) : 1.0f;
; #pragma unroll
;                     for (int bj = 0; bj < 2; ++bj) { const f32x4 v0 = acc[ai][bj][m][0] * rr * gv[bj][0], v1 = acc[ai][bj][m][1] * rr * gv[bj][1];
;                         const int dcol = 64 * head + 32 * bj + 8 * fq;
;                         u32x4 w; w.x = cvt_pk_bf16(v0[0], v0[1]); w.y = cvt_pk_bf16(v0[2], v0[3]); w.z = cvt_pk_bf16(v1[0], v1[1]); w.w = cvt_pk_bf16(v1[2], v1[3]);
;                         *(u32x4*)(dst + (size_t)row * 512 + dcol) = w;
;                         if (fo) { float* op = fo + (size_t)orow * 512 + dcol; if (prompt) { __builtin_nontemporal_store(v0, (f32x4*)op); __builtin_nontemporal_store(v1, (f32x4*)(op + 4)); } else { *(f32x4*)op = v0; *(f32x4*)(op + 4) = v1; } } } }
.LBB0_179:
	v_or_b32_e32 v146, 32, v166
	s_waitcnt lgkmcnt(0)
	v_add_u32_e32 v147, 0xffffc020, v166
	v_cndmask_b32_e64 v148, v147, v146, s[10:11]
	v_ashrrev_i32_e32 v147, 31, v146
	v_lshlrev_b64 v[146:147], 10, v[146:147]
	v_ashrrev_i32_e32 v149, 31, v148
	v_lshl_add_u64 v[174:175], s[90:91], 0, v[146:147]
	v_lshlrev_b64 v[146:147], 11, v[148:149]
	v_lshl_add_u64 v[170:171], s[12:13], 0, v[146:147]
	v_pk_mul_f32 v[146:147], v[96:97], v[172:173] op_sel_hi:[1,0]
	v_pk_mul_f32 v[150:151], v[94:95], v[172:173] op_sel_hi:[1,0]
	v_pk_mul_f32 v[148:149], v[144:145], v[146:147]
	v_pk_mul_f32 v[146:147], v[142:143], v[150:151]
	v_pk_mul_f32 v[150:151], v[92:93], v[172:173] op_sel_hi:[1,0]
	v_pk_mul_f32 v[186:187], v[90:91], v[172:173] op_sel_hi:[1,0]
	v_pk_mul_f32 v[152:153], v[136:137], v[150:151]
	v_pk_mul_f32 v[150:151], v[134:135], v[186:187]
	v_lshl_add_u64 v[174:175], v[174:175], 0, v[156:157]
	s_and_b64 vcc, exec, s[8:9]
	v_cvt_pk_bf16_f32 v186, v146, v147
	v_cvt_pk_bf16_f32 v187, v148, v149
	v_cvt_pk_bf16_f32 v188, v150, v151
	v_cvt_pk_bf16_f32 v189, v152, v153
	s_waitcnt lgkmcnt(0)
	global_store_dwordx4 v224, v[230:233], s[98:99] offset:64
	s_nop 0
	v_readfirstlane_b32 s98, v174
	v_readfirstlane_b32 s99, v175
	ds_write_b128 v222, v[186:189]
	ds_read_b128 v[230:233], v223
	s_cbranch_vccnz .LBB0_181
	v_mov_b32_e32 v169, v157
	v_lshl_add_u64 v[186:187], v[170:171], 0, v[168:169]
	s_waitcnt lgkmcnt(0)
	global_store_dwordx4 v227, v[234:237], s[100:101]
	global_store_dwordx4 v228, v[238:241], s[100:101]
	s_nop 0
	v_readfirstlane_b32 s100, v186
	v_readfirstlane_b32 s101, v187
	ds_write_b128 v225, v[146:149]
	ds_write_b128 v225, v[150:153] offset:16
	ds_read_b128 v[234:237], v226
	ds_read_b128 v[238:241], v226 offset:1024
.LBB0_181:
	v_mov_b32_e32 v173, v172
	s_nop 0
	v_mov_b32_e32 v150, v172
	v_mov_b32_e32 v151, v172
	v_pk_mul_f32 v[146:147], v[88:89], v[150:151]
	v_pk_mul_f32 v[152:153], v[86:87], v[172:173]
	v_pk_mul_f32 v[150:151], v[84:85], v[150:151]
	v_pk_mul_f32 v[172:173], v[82:83], v[172:173]
	v_pk_mul_f32 v[148:149], v[140:141], v[146:147]
	v_pk_mul_f32 v[146:147], v[138:139], v[152:153]
	v_pk_mul_f32 v[152:153], v[132:133], v[150:151]
	v_pk_mul_f32 v[150:151], v[130:131], v[172:173]
	s_and_b64 vcc, exec, s[8:9]
	v_cvt_pk_bf16_f32 v186, v146, v147
	v_cvt_pk_bf16_f32 v187, v148, v149
	v_cvt_pk_bf16_f32 v188, v150, v151
	v_cvt_pk_bf16_f32 v189, v152, v153
	s_waitcnt lgkmcnt(0)
	global_store_dwordx4 v224, v[230:233], s[98:99]
	s_nop 0
	v_readfirstlane_b32 s98, v174
	v_readfirstlane_b32 s99, v175
	ds_write_b128 v222, v[186:189]
	ds_read_b128 v[230:233], v223
	s_cbranch_vccnz .LBB0_183
	v_mov_b32_e32 v169, v157
	v_lshl_add_u64 v[170:171], v[170:171], 0, v[168:169]
	s_waitcnt lgkmcnt(0)
	global_store_dwordx4 v227, v[242:245], s[50:51] offset:128
	global_store_dwordx4 v228, v[246:249], s[50:51] offset:128
	s_nop 0
	v_readfirstlane_b32 s50, v170
	v_readfirstlane_b32 s51, v171
	ds_write_b128 v225, v[146:149]
	ds_write_b128 v225, v[150:153] offset:16
	ds_read_b128 v[242:245], v226
	ds_read_b128 v[246:249], v226 offset:1024

; __device__ __forceinline__ unsigned cvt_pk_bf16(float lo, float hi) { unsigned r; asm volatile("v_cvt_pk_bf16_f32 %0, %1, %2" : "=v"(r) : "v"(lo), "v"(hi)); return r; }
; __device__ __forceinline__ float quad_sum(float s) { s += __shfl_xor(s, 16); s += __shfl_xor(s, 32); return s; }
;     __device__ __forceinline__ void operator()(const f32x4 (&acc)[2][2][4][2], const Unit& u, int wr, int wc, int fr, int fq) const {
;     ...
;                 for (int m = 0; m < 4; ++m) { const int row = row0 + ai * HALF + m * 16; const int orow = prompt ? row : row - XM_PROMPT;
;                     float ss = 0.f;
; #pragma unroll
;                     for (int bj = 0; bj < 2; ++bj)
; #pragma unroll
;                         for (int n = 0; n < 2; ++n) { const f32x4 x = acc[ai][bj][m][n]; ss += (x[0] * x[0] + x[1] * x[1]) + (x[2] * x[2] + x[3] * x[3]); }
;                     ss = quad_sum(ss);
;                     const float rr = (sec < 4) ? post * (1.0f / sqrtf(ss * (1.0f / 64.0f) + 1e-6f)) : 1.0f;
; #pragma unroll
;                     for (int bj = 0; bj < 2; ++bj) { const f32x4 v0 = acc[ai][bj][m][0] * rr * gv[bj][0], v1 = acc[ai][bj][m][1] * rr * gv[bj][1];
;                         const int dcol = 64 * head + 32 * bj + 8 * fq;
;                         u32x4 w; w.x = cvt_pk_bf16(v0[0], v0[1]); w.y = cvt_pk_bf16(v0[2], v0[3]); w.z = cvt_pk_bf16(v1[0], v1[1]); w.w = cvt_pk_bf16(v1[2], v1[3]);
;                         *(u32x4*)(dst + (size_t)row * 512 + dcol) = w;
;                         if (fo) { float* op = fo + (size_t)orow * 512 + dcol; if (prompt) { __builtin_nontemporal_store(v0, (f32x4*)op); __builtin_nontemporal_store(v1, (f32x4*)(op + 4)); } else { *(f32x4*)op = v0; *(f32x4*)(op + 4) = v1; } } } }
.LBB0_185:
	v_or_b32_e32 v146, 48, v166
	s_waitcnt lgkmcnt(0)
	v_add_u32_e32 v147, 0xffffc030, v166
	v_cndmask_b32_e64 v148, v147, v146, s[10:11]
	v_ashrrev_i32_e32 v147, 31, v146
	v_lshlrev_b64 v[146:147], 10, v[146:147]
	v_ashrrev_i32_e32 v149, 31, v148
	v_lshl_add_u64 v[174:175], s[90:91], 0, v[146:147]
	v_lshlrev_b64 v[146:147], 11, v[148:149]
	v_lshl_add_u64 v[170:171], s[12:13], 0, v[146:147]
	v_pk_mul_f32 v[146:147], v[80:81], v[172:173] op_sel_hi:[1,0]
	v_pk_mul_f32 v[150:151], v[78:79], v[172:173] op_sel_hi:[1,0]
	v_pk_mul_f32 v[148:149], v[144:145], v[146:147]
	v_pk_mul_f32 v[146:147], v[142:143], v[150:151]
	v_pk_mul_f32 v[150:151], v[76:77], v[172:173] op_sel_hi:[1,0]
	v_pk_mul_f32 v[186:187], v[74:75], v[172:173] op_sel_hi:[1,0]
	v_pk_mul_f32 v[152:153], v[136:137], v[150:151]
	v_pk_mul_f32 v[150:151], v[134:135], v[186:187]
	v_lshl_add_u64 v[174:175], v[174:175], 0, v[156:157]
	s_and_b64 vcc, exec, s[8:9]
	v_cvt_pk_bf16_f32 v186, v146, v147
	v_cvt_pk_bf16_f32 v187, v148, v149
	v_cvt_pk_bf16_f32 v188, v150, v151
	v_cvt_pk_bf16_f32 v189, v152, v153
	s_waitcnt lgkmcnt(0)
	global_store_dwordx4 v224, v[230:233], s[98:99] offset:64
	s_nop 0
	v_readfirstlane_b32 s98, v174
	v_readfirstlane_b32 s99, v175
	ds_write_b128 v222, v[186:189]
	ds_read_b128 v[230:233], v223
	s_cbranch_vccnz .LBB0_187
	v_mov_b32_e32 v169, v157
	v_lshl_add_u64 v[186:187], v[170:171], 0, v[168:169]
	s_waitcnt lgkmcnt(0)
	global_store_dwordx4 v227, v[234:237], s[100:101]
	global_store_dwordx4 v228, v[238:241], s[100:101]
	s_nop 0
	v_readfirstlane_b32 s100, v186
	v_readfirstlane_b32 s101, v187
	ds_write_b128 v225, v[146:149]
	ds_write_b128 v225, v[150:153] offset:16
	ds_read_b128 v[234:237], v226
	ds_read_b128 v[238:241], v226 offset:1024
.LBB0_187:
	v_mov_b32_e32 v173, v172
	s_nop 0
	v_mov_b32_e32 v150, v172
	v_mov_b32_e32 v151, v172
	v_pk_mul_f32 v[146:147], v[72:73], v[150:151]
	v_pk_mul_f32 v[152:153], v[70:71], v[172:173]
	v_pk_mul_f32 v[150:151], v[68:69], v[150:151]
	v_pk_mul_f32 v[172:173], v[66:67], v[172:173]
	v_pk_mul_f32 v[148:149], v[140:141], v[146:147]
	v_pk_mul_f32 v[146:147], v[138:139], v[152:153]
	v_pk_mul_f32 v[152:153], v[132:133], v[150:151]
	v_pk_mul_f32 v[150:151], v[130:131], v[172:173]
	s_and_b64 vcc, exec, s[8:9]
	v_cvt_pk_bf16_f32 v186, v146, v147
	v_cvt_pk_bf16_f32 v187, v148, v149
	v_cvt_pk_bf16_f32 v188, v150, v151
	v_cvt_pk_bf16_f32 v189, v152, v153
	s_waitcnt lgkmcnt(0)
	global_store_dwordx4 v224, v[230:233], s[98:99]
	s_nop 0
	v_readfirstlane_b32 s98, v174
	v_readfirstlane_b32 s99, v175
	ds_write_b128 v222, v[186:189]
	ds_read_b128 v[230:233], v223
	s_cbranch_vccnz .LBB0_189
	v_mov_b32_e32 v169, v157
	v_lshl_add_u64 v[170:171], v[170:171], 0, v[168:169]
	s_waitcnt lgkmcnt(0)
	global_store_dwordx4 v227, v[242:245], s[50:51] offset:128
	global_store_dwordx4 v228, v[246:249], s[50:51] offset:128
	s_nop 0
	v_readfirstlane_b32 s50, v170
	v_readfirstlane_b32 s51, v171
	ds_write_b128 v225, v[146:149]
	ds_write_b128 v225, v[150:153] offset:16
	ds_read_b128 v[242:245], v226
	ds_read_b128 v[246:249], v226 offset:1024

; __device__ __forceinline__ unsigned cvt_pk_bf16(float lo, float hi) { unsigned r; asm volatile("v_cvt_pk_bf16_f32 %0, %1, %2" : "=v"(r) : "v"(lo), "v"(hi)); return r; }
; __device__ __forceinline__ float quad_sum(float s) { s += __shfl_xor(s, 16); s += __shfl_xor(s, 32); return s; }
;     __device__ __forceinline__ void operator()(const f32x4 (&acc)[2][2][4][2], const Unit& u, int wr, int wc, int fr, int fq) const {
;     ...
;                 for (int m = 0; m < 4; ++m) { const int row = row0 + ai * HALF + m * 16; const int orow = prompt ? row : row - XM_PROMPT;
;                     float ss = 0.f;
; #pragma unroll
;                     for (int bj = 0; bj < 2; ++bj)
; #pragma unroll
;                         for (int n = 0; n < 2; ++n) { const f32x4 x = acc[ai][bj][m][n]; ss += (x[0] * x[0] + x[1] * x[1]) + (x[2] * x[2] + x[3] * x[3]); }
;                     ss = quad_sum(ss);
;                     const float rr = (sec < 4) ? post * (1.0f / sqrtf(ss * (1.0f / 64.0f) + 1e-6f)) : 1.0f;
; #pragma unroll
;                     for (int bj = 0; bj < 2; ++bj) { const f32x4 v0 = acc[ai][bj][m][0] * rr * gv[bj][0], v1 = acc[ai][bj][m][1] * rr * gv[bj][1];
;                         const int dcol = 64 * head + 32 * bj + 8 * fq;
;                         u32x4 w; w.x = cvt_pk_bf16(v0[0], v0[1]); w.y = cvt_pk_bf16(v0[2], v0[3]); w.z = cvt_pk_bf16(v1[0], v1[1]); w.w = cvt_pk_bf16(v1[2], v1[3]);
;                         *(u32x4*)(dst + (size_t)row * 512 + dcol) = w;
;                         if (fo) { float* op = fo + (size_t)orow * 512 + dcol; if (prompt) { __builtin_nontemporal_store(v0, (f32x4*)op); __builtin_nontemporal_store(v1, (f32x4*)(op + 4)); } else { *(f32x4*)op = v0; *(f32x4*)(op + 4) = v1; } } } }
.LBB0_191:
	v_add_u32_e32 v146, 0x80, v166
	s_waitcnt lgkmcnt(0)
	v_add_u32_e32 v147, 0xffffc080, v166
	v_cndmask_b32_e64 v148, v147, v146, s[10:11]
	v_ashrrev_i32_e32 v147, 31, v146
	v_lshlrev_b64 v[146:147], 10, v[146:147]
	v_ashrrev_i32_e32 v149, 31, v148
	v_lshl_add_u64 v[174:175], s[90:91], 0, v[146:147]
	v_lshlrev_b64 v[146:147], 11, v[148:149]
	v_lshl_add_u64 v[170:171], s[12:13], 0, v[146:147]
	v_pk_mul_f32 v[146:147], v[64:65], v[172:173] op_sel_hi:[1,0]
	v_pk_mul_f32 v[150:151], v[62:63], v[172:173] op_sel_hi:[1,0]
	v_pk_mul_f32 v[148:149], v[144:145], v[146:147]
	v_pk_mul_f32 v[146:147], v[142:143], v[150:151]
	v_pk_mul_f32 v[150:151], v[60:61], v[172:173] op_sel_hi:[1,0]
	v_pk_mul_f32 v[186:187], v[58:59], v[172:173] op_sel_hi:[1,0]
	v_pk_mul_f32 v[152:153], v[136:137], v[150:151]
	v_pk_mul_f32 v[150:151], v[134:135], v[186:187]
	v_lshl_add_u64 v[174:175], v[174:175], 0, v[156:157]
	s_and_b64 vcc, exec, s[8:9]
	v_cvt_pk_bf16_f32 v186, v146, v147
	v_cvt_pk_bf16_f32 v187, v148, v149
	v_cvt_pk_bf16_f32 v188, v150, v151
	v_cvt_pk_bf16_f32 v189, v152, v153
	s_waitcnt lgkmcnt(0)
	global_store_dwordx4 v224, v[230:233], s[98:99] offset:64
	s_nop 0
	v_readfirstlane_b32 s98, v174
	v_readfirstlane_b32 s99, v175
	ds_write_b128 v222, v[186:189]
	ds_read_b128 v[230:233], v223
	s_cbranch_vccnz .LBB0_193
	v_mov_b32_e32 v169, v157
	v_lshl_add_u64 v[186:187], v[170:171], 0, v[168:169]
	s_waitcnt lgkmcnt(0)
	global_store_dwordx4 v227, v[234:237], s[100:101]
	global_store_dwordx4 v228, v[238:241], s[100:101]
	s_nop 0
	v_readfirstlane_b32 s100, v186
	v_readfirstlane_b32 s101, v187
	ds_write_b128 v225, v[146:149]
	ds_write_b128 v225, v[150:153] offset:16
	ds_read_b128 v[234:237], v226
	ds_read_b128 v[238:241], v226 offset:1024
.LBB0_193:
	v_mov_b32_e32 v173, v172
	s_nop 0
	v_mov_b32_e32 v150, v172
	v_mov_b32_e32 v151, v172
	v_pk_mul_f32 v[146:147], v[56:57], v[150:151]
	v_pk_mul_f32 v[152:153], v[54:55], v[172:173]
	v_pk_mul_f32 v[150:151], v[52:53], v[150:151]
	v_pk_mul_f32 v[172:173], v[50:51], v[172:173]
	v_pk_mul_f32 v[148:149], v[140:141], v[146:147]
	v_pk_mul_f32 v[146:147], v[138:139], v[152:153]
	v_pk_mul_f32 v[152:153], v[132:133], v[150:151]
	v_pk_mul_f32 v[150:151], v[130:131], v[172:173]
	s_and_b64 vcc, exec, s[8:9]
	v_cvt_pk_bf16_f32 v186, v146, v147
	v_cvt_pk_bf16_f32 v187, v148, v149
	v_cvt_pk_bf16_f32 v188, v150, v151
	v_cvt_pk_bf16_f32 v189, v152, v153
	s_waitcnt lgkmcnt(0)
	global_store_dwordx4 v224, v[230:233], s[98:99]
	s_nop 0
	v_readfirstlane_b32 s98, v174
	v_readfirstlane_b32 s99, v175
	ds_write_b128 v222, v[186:189]
	ds_read_b128 v[230:233], v223
	s_cbranch_vccnz .LBB0_195
	v_mov_b32_e32 v169, v157
	v_lshl_add_u64 v[170:171], v[170:171], 0, v[168:169]
	s_waitcnt lgkmcnt(0)
	global_store_dwordx4 v227, v[242:245], s[50:51] offset:128
	global_store_dwordx4 v228, v[246:249], s[50:51] offset:128
	s_nop 0
	v_readfirstlane_b32 s50, v170
	v_readfirstlane_b32 s51, v171
	ds_write_b128 v225, v[146:149]
	ds_write_b128 v225, v[150:153] offset:16
	ds_read_b128 v[242:245], v226
	ds_read_b128 v[246:249], v226 offset:1024

; __device__ __forceinline__ unsigned cvt_pk_bf16(float lo, float hi) { unsigned r; asm volatile("v_cvt_pk_bf16_f32 %0, %1, %2" : "=v"(r) : "v"(lo), "v"(hi)); return r; }
; __device__ __forceinline__ float quad_sum(float s) { s += __shfl_xor(s, 16); s += __shfl_xor(s, 32); return s; }
;     __device__ __forceinline__ void operator()(const f32x4 (&acc)[2][2][4][2], const Unit& u, int wr, int wc, int fr, int fq) const {
;     ...
;                 for (int m = 0; m < 4; ++m) { const int row = row0 + ai * HALF + m * 16; const int orow = prompt ? row : row - XM_PROMPT;
;                     float ss = 0.f;
; #pragma unroll
;                     for (int bj = 0; bj < 2; ++bj)
; #pragma unroll
;                         for (int n = 0; n < 2; ++n) { const f32x4 x = acc[ai][bj][m][n]; ss += (x[0] * x[0] + x[1] * x[1]) + (x[2] * x[2] + x[3] * x[3]); }
;                     ss = quad_sum(ss);
;                     const float rr = (sec < 4) ? post * (1.0f / sqrtf(ss * (1.0f / 64.0f) + 1e-6f)) : 1.0f;
; #pragma unroll
;                     for (int bj = 0; bj < 2; ++bj) { const f32x4 v0 = acc[ai][bj][m][0] * rr * gv[bj][0], v1 = acc[ai][bj][m][1] * rr * gv[bj][1];
;                         const int dcol = 64 * head + 32 * bj + 8 * fq;
;                         u32x4 w; w.x = cvt_pk_bf16(v0[0], v0[1]); w.y = cvt_pk_bf16(v0[2], v0[3]); w.z = cvt_pk_bf16(v1[0], v1[1]); w.w = cvt_pk_bf16(v1[2], v1[3]);
;                         *(u32x4*)(dst + (size_t)row * 512 + dcol) = w;
;                         if (fo) { float* op = fo + (size_t)orow * 512 + dcol; if (prompt) { __builtin_nontemporal_store(v0, (f32x4*)op); __builtin_nontemporal_store(v1, (f32x4*)(op + 4)); } else { *(f32x4*)op = v0; *(f32x4*)(op + 4) = v1; } } } }
.LBB0_197:
	v_add_u32_e32 v146, 0x90, v166
	s_waitcnt lgkmcnt(0)
	v_add_u32_e32 v147, 0xffffc090, v166
	v_cndmask_b32_e64 v148, v147, v146, s[10:11]
	v_ashrrev_i32_e32 v147, 31, v146
	v_lshlrev_b64 v[146:147], 10, v[146:147]
	v_ashrrev_i32_e32 v149, 31, v148
	v_lshl_add_u64 v[174:175], s[90:91], 0, v[146:147]
	v_lshlrev_b64 v[146:147], 11, v[148:149]
	v_lshl_add_u64 v[170:171], s[12:13], 0, v[146:147]
	v_pk_mul_f32 v[146:147], v[48:49], v[172:173] op_sel_hi:[1,0]
	v_pk_mul_f32 v[150:151], v[46:47], v[172:173] op_sel_hi:[1,0]
	v_pk_mul_f32 v[148:149], v[144:145], v[146:147]
	v_pk_mul_f32 v[146:147], v[142:143], v[150:151]
	v_pk_mul_f32 v[150:151], v[44:45], v[172:173] op_sel_hi:[1,0]
	v_pk_mul_f32 v[186:187], v[42:43], v[172:173] op_sel_hi:[1,0]
	v_pk_mul_f32 v[152:153], v[136:137], v[150:151]
	v_pk_mul_f32 v[150:151], v[134:135], v[186:187]
	v_lshl_add_u64 v[174:175], v[174:175], 0, v[156:157]
	s_and_b64 vcc, exec, s[8:9]
	v_cvt_pk_bf16_f32 v186, v146, v147
	v_cvt_pk_bf16_f32 v187, v148, v149
	v_cvt_pk_bf16_f32 v188, v150, v151
	v_cvt_pk_bf16_f32 v189, v152, v153
	s_waitcnt lgkmcnt(0)
	global_store_dwordx4 v224, v[230:233], s[98:99] offset:64
	s_nop 0
	v_readfirstlane_b32 s98, v174
	v_readfirstlane_b32 s99, v175
	ds_write_b128 v222, v[186:189]
	ds_read_b128 v[230:233], v223
	s_cbranch_vccnz .LBB0_199
	v_mov_b32_e32 v169, v157
	v_lshl_add_u64 v[186:187], v[170:171], 0, v[168:169]
	s_waitcnt lgkmcnt(0)
	global_store_dwordx4 v227, v[234:237], s[100:101]
	global_store_dwordx4 v228, v[238:241], s[100:101]
	s_nop 0
	v_readfirstlane_b32 s100, v186
	v_readfirstlane_b32 s101, v187
	ds_write_b128 v225, v[146:149]
	ds_write_b128 v225, v[150:153] offset:16
	ds_read_b128 v[234:237], v226
	ds_read_b128 v[238:241], v226 offset:1024
.LBB0_199:
	v_mov_b32_e32 v173, v172
	s_nop 0
	v_mov_b32_e32 v150, v172
	v_mov_b32_e32 v151, v172
	v_pk_mul_f32 v[146:147], v[40:41], v[150:151]
	v_pk_mul_f32 v[152:153], v[38:39], v[172:173]
	v_pk_mul_f32 v[150:151], v[36:37], v[150:151]
	v_pk_mul_f32 v[172:173], v[34:35], v[172:173]
	v_pk_mul_f32 v[148:149], v[140:141], v[146:147]
	v_pk_mul_f32 v[146:147], v[138:139], v[152:153]
	v_pk_mul_f32 v[152:153], v[132:133], v[150:151]
	v_pk_mul_f32 v[150:151], v[130:131], v[172:173]
	s_and_b64 vcc, exec, s[8:9]
	v_cvt_pk_bf16_f32 v186, v146, v147
	v_cvt_pk_bf16_f32 v187, v148, v149
	v_cvt_pk_bf16_f32 v188, v150, v151
	v_cvt_pk_bf16_f32 v189, v152, v153
	s_waitcnt lgkmcnt(0)
	global_store_dwordx4 v224, v[230:233], s[98:99]
	s_nop 0
	v_readfirstlane_b32 s98, v174
	v_readfirstlane_b32 s99, v175
	ds_write_b128 v222, v[186:189]
	ds_read_b128 v[230:233], v223
	s_cbranch_vccnz .LBB0_201
	v_mov_b32_e32 v169, v157
	v_lshl_add_u64 v[170:171], v[170:171], 0, v[168:169]
	s_waitcnt lgkmcnt(0)
	global_store_dwordx4 v227, v[242:245], s[50:51] offset:128
	global_store_dwordx4 v228, v[246:249], s[50:51] offset:128
	s_nop 0
	v_readfirstlane_b32 s50, v170
	v_readfirstlane_b32 s51, v171
	ds_write_b128 v225, v[146:149]
	ds_write_b128 v225, v[150:153] offset:16
	ds_read_b128 v[242:245], v226
	ds_read_b128 v[246:249], v226 offset:1024

; __device__ __forceinline__ unsigned cvt_pk_bf16(float lo, float hi) { unsigned r; asm volatile("v_cvt_pk_bf16_f32 %0, %1, %2" : "=v"(r) : "v"(lo), "v"(hi)); return r; }
; __device__ __forceinline__ float quad_sum(float s) { s += __shfl_xor(s, 16); s += __shfl_xor(s, 32); return s; }
;     __device__ __forceinline__ void operator()(const f32x4 (&acc)[2][2][4][2], const Unit& u, int wr, int wc, int fr, int fq) const {
;     ...
;                 for (int m = 0; m < 4; ++m) { const int row = row0 + ai * HALF + m * 16; const int orow = prompt ? row : row - XM_PROMPT;
;                     float ss = 0.f;
; #pragma unroll
;                     for (int bj = 0; bj < 2; ++bj)
; #pragma unroll
;                         for (int n = 0; n < 2; ++n) { const f32x4 x = acc[ai][bj][m][n]; ss += (x[0] * x[0] + x[1] * x[1]) + (x[2] * x[2] + x[3] * x[3]); }
;                     ss = quad_sum(ss);
;                     const float rr = (sec < 4) ? post * (1.0f / sqrtf(ss * (1.0f / 64.0f) + 1e-6f)) : 1.0f;
; #pragma unroll
;                     for (int bj = 0; bj < 2; ++bj) { const f32x4 v0 = acc[ai][bj][m][0] * rr * gv[bj][0], v1 = acc[ai][bj][m][1] * rr * gv[bj][1];
;                         const int dcol = 64 * head + 32 * bj + 8 * fq;
;                         u32x4 w; w.x = cvt_pk_bf16(v0[0], v0[1]); w.y = cvt_pk_bf16(v0[2], v0[3]); w.z = cvt_pk_bf16(v1[0], v1[1]); w.w = cvt_pk_bf16(v1[2], v1[3]);
;                         *(u32x4*)(dst + (size_t)row * 512 + dcol) = w;
;                         if (fo) { float* op = fo + (size_t)orow * 512 + dcol; if (prompt) { __builtin_nontemporal_store(v0, (f32x4*)op); __builtin_nontemporal_store(v1, (f32x4*)(op + 4)); } else { *(f32x4*)op = v0; *(f32x4*)(op + 4) = v1; } } } }
.LBB0_203:
	v_add_u32_e32 v146, 0xa0, v166
	s_waitcnt lgkmcnt(0)
	v_add_u32_e32 v147, 0xffffc0a0, v166
	v_cndmask_b32_e64 v148, v147, v146, s[10:11]
	v_ashrrev_i32_e32 v147, 31, v146
	v_lshlrev_b64 v[146:147], 10, v[146:147]
	v_ashrrev_i32_e32 v149, 31, v148
	v_lshl_add_u64 v[174:175], s[90:91], 0, v[146:147]
	v_lshlrev_b64 v[146:147], 11, v[148:149]
	v_lshl_add_u64 v[170:171], s[12:13], 0, v[146:147]
	v_pk_mul_f32 v[146:147], v[32:33], v[172:173] op_sel_hi:[1,0]
	v_pk_mul_f32 v[150:151], v[30:31], v[172:173] op_sel_hi:[1,0]
	v_pk_mul_f32 v[148:149], v[144:145], v[146:147]
	v_pk_mul_f32 v[146:147], v[142:143], v[150:151]
	v_pk_mul_f32 v[150:151], v[28:29], v[172:173] op_sel_hi:[1,0]
	v_pk_mul_f32 v[186:187], v[26:27], v[172:173] op_sel_hi:[1,0]
	v_pk_mul_f32 v[152:153], v[136:137], v[150:151]
	v_pk_mul_f32 v[150:151], v[134:135], v[186:187]
	v_lshl_add_u64 v[174:175], v[174:175], 0, v[156:157]
	s_and_b64 vcc, exec, s[8:9]
	v_cvt_pk_bf16_f32 v186, v146, v147
	v_cvt_pk_bf16_f32 v187, v148, v149
	v_cvt_pk_bf16_f32 v188, v150, v151
	v_cvt_pk_bf16_f32 v189, v152, v153
	s_waitcnt lgkmcnt(0)
	global_store_dwordx4 v224, v[230:233], s[98:99] offset:64
	s_nop 0
	v_readfirstlane_b32 s98, v174
	v_readfirstlane_b32 s99, v175
	ds_write_b128 v222, v[186:189]
	ds_read_b128 v[230:233], v223
	s_cbranch_vccnz .LBB0_205
	v_mov_b32_e32 v169, v157
	v_lshl_add_u64 v[186:187], v[170:171], 0, v[168:169]
	s_waitcnt lgkmcnt(0)
	global_store_dwordx4 v227, v[234:237], s[100:101]
	global_store_dwordx4 v228, v[238:241], s[100:101]
	s_nop 0
	v_readfirstlane_b32 s100, v186
	v_readfirstlane_b32 s101, v187
	ds_write_b128 v225, v[146:149]
	ds_write_b128 v225, v[150:153] offset:16
	ds_read_b128 v[234:237], v226
	ds_read_b128 v[238:241], v226 offset:1024
.LBB0_205:
	v_mov_b32_e32 v173, v172
	s_nop 0
	v_mov_b32_e32 v150, v172
	v_mov_b32_e32 v151, v172
	v_pk_mul_f32 v[146:147], v[24:25], v[150:151]
	v_pk_mul_f32 v[152:153], v[22:23], v[172:173]
	v_pk_mul_f32 v[150:151], v[20:21], v[150:151]
	v_pk_mul_f32 v[172:173], v[18:19], v[172:173]
	v_pk_mul_f32 v[148:149], v[140:141], v[146:147]
	v_pk_mul_f32 v[146:147], v[138:139], v[152:153]
	v_pk_mul_f32 v[152:153], v[132:133], v[150:151]
	v_pk_mul_f32 v[150:151], v[130:131], v[172:173]
	s_and_b64 vcc, exec, s[8:9]
	v_cvt_pk_bf16_f32 v186, v146, v147
	v_cvt_pk_bf16_f32 v187, v148, v149
	v_cvt_pk_bf16_f32 v188, v150, v151
	v_cvt_pk_bf16_f32 v189, v152, v153
	s_waitcnt lgkmcnt(0)
	global_store_dwordx4 v224, v[230:233], s[98:99]
	s_nop 0
	v_readfirstlane_b32 s98, v174
	v_readfirstlane_b32 s99, v175
	ds_write_b128 v222, v[186:189]
	ds_read_b128 v[230:233], v223
	s_cbranch_vccnz .LBB0_207
	v_mov_b32_e32 v169, v157
	v_lshl_add_u64 v[170:171], v[170:171], 0, v[168:169]
	s_waitcnt lgkmcnt(0)
	global_store_dwordx4 v227, v[242:245], s[50:51] offset:128
	global_store_dwordx4 v228, v[246:249], s[50:51] offset:128
	s_nop 0
	v_readfirstlane_b32 s50, v170
	v_readfirstlane_b32 s51, v171
	ds_write_b128 v225, v[146:149]
	ds_write_b128 v225, v[150:153] offset:16
	ds_read_b128 v[242:245], v226
	ds_read_b128 v[246:249], v226 offset:1024

; __device__ __forceinline__ unsigned cvt_pk_bf16(float lo, float hi) { unsigned r; asm volatile("v_cvt_pk_bf16_f32 %0, %1, %2" : "=v"(r) : "v"(lo), "v"(hi)); return r; }
; __device__ __forceinline__ float quad_sum(float s) { s += __shfl_xor(s, 16); s += __shfl_xor(s, 32); return s; }
;     __device__ __forceinline__ void operator()(const f32x4 (&acc)[2][2][4][2], const Unit& u, int wr, int wc, int fr, int fq) const {
;     ...
;                 for (int m = 0; m < 4; ++m) { const int row = row0 + ai * HALF + m * 16; const int orow = prompt ? row : row - XM_PROMPT;
;                     float ss = 0.f;
; #pragma unroll
;                     for (int bj = 0; bj < 2; ++bj)
; #pragma unroll
;                         for (int n = 0; n < 2; ++n) { const f32x4 x = acc[ai][bj][m][n]; ss += (x[0] * x[0] + x[1] * x[1]) + (x[2] * x[2] + x[3] * x[3]); }
;                     ss = quad_sum(ss);
;                     const float rr = (sec < 4) ? post * (1.0f / sqrtf(ss * (1.0f / 64.0f) + 1e-6f)) : 1.0f;
; #pragma unroll
;                     for (int bj = 0; bj < 2; ++bj) { const f32x4 v0 = acc[ai][bj][m][0] * rr * gv[bj][0], v1 = acc[ai][bj][m][1] * rr * gv[bj][1];
;                         const int dcol = 64 * head + 32 * bj + 8 * fq;
;                         u32x4 w; w.x = cvt_pk_bf16(v0[0], v0[1]); w.y = cvt_pk_bf16(v0[2], v0[3]); w.z = cvt_pk_bf16(v1[0], v1[1]); w.w = cvt_pk_bf16(v1[2], v1[3]);
;                         *(u32x4*)(dst + (size_t)row * 512 + dcol) = w;
;                         if (fo) { float* op = fo + (size_t)orow * 512 + dcol; if (prompt) { __builtin_nontemporal_store(v0, (f32x4*)op); __builtin_nontemporal_store(v1, (f32x4*)(op + 4)); } else { *(f32x4*)op = v0; *(f32x4*)(op + 4) = v1; } } } }
.LBB0_209:
	v_add_u32_e32 v146, 0xb0, v166
	s_waitcnt lgkmcnt(0)
	v_add_u32_e32 v147, 0xffffc0b0, v166
	v_cndmask_b32_e64 v150, v147, v146, s[10:11]
	v_ashrrev_i32_e32 v147, 31, v146
	v_lshlrev_b64 v[146:147], 10, v[146:147]
	v_ashrrev_i32_e32 v151, 31, v150
	v_lshl_add_u64 v[152:153], s[90:91], 0, v[146:147]
	v_lshlrev_b64 v[146:147], 11, v[150:151]
	v_pk_mul_f32 v[150:151], v[16:17], v[148:149] op_sel_hi:[1,0]
	v_pk_mul_f32 v[170:171], v[14:15], v[148:149] op_sel_hi:[1,0]
	v_pk_mul_f32 v[144:145], v[144:145], v[150:151]
	v_pk_mul_f32 v[142:143], v[142:143], v[170:171]
	v_pk_mul_f32 v[150:151], v[12:13], v[148:149] op_sel_hi:[1,0]
	v_pk_mul_f32 v[170:171], v[10:11], v[148:149] op_sel_hi:[1,0]
	v_lshl_add_u64 v[146:147], s[12:13], 0, v[146:147]
	v_pk_mul_f32 v[136:137], v[136:137], v[150:151]
	v_pk_mul_f32 v[134:135], v[134:135], v[170:171]
	v_lshl_add_u64 v[150:151], v[152:153], 0, v[156:157]
	s_and_b64 vcc, exec, s[8:9]
	v_cvt_pk_bf16_f32 v170, v142, v143
	v_cvt_pk_bf16_f32 v171, v144, v145
	v_cvt_pk_bf16_f32 v172, v134, v135
	v_cvt_pk_bf16_f32 v173, v136, v137
	s_waitcnt lgkmcnt(0)
	global_store_dwordx4 v224, v[230:233], s[98:99] offset:64
	s_nop 0
	v_readfirstlane_b32 s98, v150
	v_readfirstlane_b32 s99, v151
	ds_write_b128 v222, v[170:173]
	ds_read_b128 v[230:233], v223
	s_cbranch_vccnz .LBB0_211
	v_mov_b32_e32 v169, v157
	v_lshl_add_u64 v[152:153], v[146:147], 0, v[168:169]
	s_waitcnt lgkmcnt(0)
	global_store_dwordx4 v227, v[234:237], s[100:101]
	global_store_dwordx4 v228, v[238:241], s[100:101]
	s_nop 0
	v_readfirstlane_b32 s100, v152
	v_readfirstlane_b32 s101, v153
	ds_write_b128 v225, v[142:145]
	ds_write_b128 v225, v[134:137] offset:16
	ds_read_b128 v[234:237], v226
	ds_read_b128 v[238:241], v226 offset:1024
	s_nop 1
	s_waitcnt lgkmcnt(0)
	global_store_dwordx4 v227, v[234:237], s[100:101]
	global_store_dwordx4 v228, v[238:241], s[100:101]
.LBB0_211:
	v_mov_b32_e32 v149, v148
	v_mov_b32_e32 v142, v148
	v_mov_b32_e32 v143, v148
	v_pk_mul_f32 v[134:135], v[8:9], v[142:143]
	v_pk_mul_f32 v[144:145], v[6:7], v[148:149]
	v_pk_mul_f32 v[136:137], v[140:141], v[134:135]
	v_pk_mul_f32 v[134:135], v[138:139], v[144:145]
	v_pk_mul_f32 v[138:139], v[4:5], v[142:143]
	v_pk_mul_f32 v[140:141], v[2:3], v[148:149]
	v_pk_mul_f32 v[132:133], v[132:133], v[138:139]
	v_pk_mul_f32 v[130:131], v[130:131], v[140:141]
	s_and_b64 vcc, exec, s[8:9]
	v_cvt_pk_bf16_f32 v138, v134, v135
	v_cvt_pk_bf16_f32 v139, v136, v137
	v_cvt_pk_bf16_f32 v140, v130, v131
	v_cvt_pk_bf16_f32 v141, v132, v133
	s_waitcnt lgkmcnt(0)
	global_store_dwordx4 v224, v[230:233], s[98:99]
	s_nop 0
	v_readfirstlane_b32 s98, v150
	v_readfirstlane_b32 s99, v151
	ds_write_b128 v222, v[138:141]
	ds_read_b128 v[230:233], v223
	s_nop 1
	s_waitcnt lgkmcnt(0)
	global_store_dwordx4 v224, v[230:233], s[98:99] offset:64
	s_cbranch_vccnz .LBB0_213
	v_mov_b32_e32 v169, v157
	v_lshl_add_u64 v[138:139], v[146:147], 0, v[168:169]
	s_waitcnt lgkmcnt(0)
	global_store_dwordx4 v227, v[242:245], s[50:51] offset:128
	global_store_dwordx4 v228, v[246:249], s[50:51] offset:128
	s_nop 0
	v_readfirstlane_b32 s50, v138
	v_readfirstlane_b32 s51, v139
	ds_write_b128 v225, v[134:137]
	ds_write_b128 v225, v[130:133] offset:16
	ds_read_b128 v[242:245], v226
	ds_read_b128 v[246:249], v226 offset:1024
	s_nop 1
	s_waitcnt lgkmcnt(0)
	global_store_dwordx4 v227, v[242:245], s[50:51] offset:128
	global_store_dwordx4 v228, v[246:249], s[50:51] offset:128

; __device__ __forceinline__ unsigned cvt_pk_bf16(float lo, float hi) { unsigned r; asm volatile("v_cvt_pk_bf16_f32 %0, %1, %2" : "=v"(r) : "v"(lo), "v"(hi)); return r; }
; __device__ __forceinline__ float gelu_t(float x) { const float u = 0.7978845608028654f * (x + 0.044715f * x * x * x); return x * fast_rcp(1.0f + fast_exp2(-2.8853900817779268f * u)); }
;     __device__ __forceinline__ void operator()(const f32x4 (&acc)[2][2][4][2], const Unit& u, int wr, int wc, int fr, int fq) const {
;     ...
;             bf16_t* dst = (bf16_t*)(ws + ((pn < 2) ? EW_U : EW_GV)); float* st1 = (float*)ws + EC_ST1; float* st2 = (float*)ws + EC_ST2; const int col0 = (pn & 1) * 256 + wc * 32 + 8 * fq; const bool stats = pn >= 2;
; #pragma unroll
;             for (int ai = 0; ai < 2; ++ai)
; #pragma unroll
;                 for (int m = 0; m < 4; ++m) { const int row = row0 + ai * HALF + m * 16; bf16_t* rowp = dst + (size_t)row * 512 + col0; float s1 = 0.f, s2 = 0.f;
; #pragma unroll
;                     for (int bj = 0; bj < 2; ++bj) { f32x4 v0 = acc[ai][bj][m][0], v1 = acc[ai][bj][m][1];
; #pragma unroll
;                         for (int j = 0; j < 4; ++j) { v0[j] = gelu_t(v0[j]); v1[j] = gelu_t(v1[j]); }
;                         s1 += (v0[0] + v0[1]) + (v0[2] + v0[3]) + (v1[0] + v1[1]) + (v1[2] + v1[3]);
;                         s2 += (v0[0] * v0[0] + v0[1] * v0[1]) + (v0[2] * v0[2] + v0[3] * v0[3]) + (v1[0] * v1[0] + v1[1] * v1[1]) + (v1[2] * v1[2] + v1[3] * v1[3]);
;                         u32x4 w; w.x = cvt_pk_bf16(v0[0], v0[1]); w.y = cvt_pk_bf16(v0[2], v0[3]); w.z = cvt_pk_bf16(v1[0], v1[1]); w.w = cvt_pk_bf16(v1[2], v1[3]);
;                         *(u32x4*)(rowp + bj * HALF) = w; }
.LBB0_214:
	v_mul_f32_e32 v134, 0x3d372713, v126
	v_mul_f32_e32 v134, v126, v134
	v_fma_f32 v134, v126, v134, v126
	v_mul_f32_e32 v134, 0x3f4c422a, v134
	v_mul_f32_e32 v134, 0xc038aa3b, v134
	v_exp_f32_e32 v134, v134
	s_cmp_lt_i32 s88, 2
	s_cselect_b64 s[6:7], -1, 0
	s_and_b64 vcc, s[6:7], exec
	v_add_f32_e32 v134, 1.0, v134
	v_rcp_f32_e32 v134, v134
	s_mov_b32 s6, 0x4200000
	s_cselect_b32 s6, s6, 0x5300000
	v_readlane_b32 s8, v251, 4
	v_mul_f32_e32 v126, v126, v134
	v_mul_f32_e32 v134, 0x3d372713, v122
	v_mul_f32_e32 v134, v122, v134
	v_fma_f32 v134, v122, v134, v122
	v_mul_f32_e32 v134, 0x3f4c422a, v134
	v_mul_f32_e32 v134, 0xc038aa3b, v134
	v_exp_f32_e32 v134, v134
	v_readlane_b32 s9, v251, 5
	s_add_u32 s6, s8, s6
	s_addc_u32 s7, s9, 0
	v_add_f32_e32 v134, 1.0, v134
	v_rcp_f32_e32 v134, v134
	s_lshl_b32 s8, s88, 8
	s_and_b32 s8, s8, 0x100
	v_or_b32_e32 v130, s8, v176
	v_mul_f32_e32 v122, v122, v134
	v_mul_f32_e32 v134, 0x3d372713, v127
	v_mul_f32_e32 v134, v127, v134
	v_fma_f32 v134, v127, v134, v127
	v_mul_f32_e32 v134, 0x3f4c422a, v134
	v_mul_f32_e32 v134, 0xc038aa3b, v134
	v_exp_f32_e32 v134, v134
	v_lshlrev_b32_e32 v156, 1, v130
	v_ashrrev_i32_e32 v167, 31, v166
	v_lshl_add_u64 v[130:131], s[6:7], 0, v[156:157]
	v_add_f32_e32 v134, 1.0, v134
	v_rcp_f32_e32 v134, v134
	v_lshlrev_b64 v[132:133], 10, v[166:167]
	v_lshl_add_u64 v[132:133], v[130:131], 0, v[132:133]
	s_cmp_gt_i32 s88, 1
	v_mul_f32_e32 v127, v127, v134
	v_mul_f32_e32 v134, 0x3d372713, v123
	v_mul_f32_e32 v134, v123, v134
	v_fma_f32 v134, v123, v134, v123
	v_mul_f32_e32 v134, 0x3f4c422a, v134
	v_mul_f32_e32 v134, 0xc038aa3b, v134
	v_exp_f32_e32 v134, v134
	s_cselect_b64 s[8:9], -1, 0
	v_add_f32_e32 v134, 1.0, v134
	v_rcp_f32_e32 v134, v134
	s_nop 0
	v_mul_f32_e32 v123, v123, v134
	v_mul_f32_e32 v134, 0x3d372713, v128
	v_mul_f32_e32 v134, v128, v134
	v_fma_f32 v134, v128, v134, v128
	v_mul_f32_e32 v134, 0x3f4c422a, v134
	v_mul_f32_e32 v134, 0xc038aa3b, v134
	v_exp_f32_e32 v134, v134
	s_nop 0
	v_add_f32_e32 v134, 1.0, v134
	v_rcp_f32_e32 v134, v134
	s_nop 0
	v_mul_f32_e32 v128, v128, v134
	v_mul_f32_e32 v134, 0x3d372713, v124
	v_mul_f32_e32 v134, v124, v134
	v_fma_f32 v134, v124, v134, v124
	v_mul_f32_e32 v134, 0x3f4c422a, v134
	v_mul_f32_e32 v134, 0xc038aa3b, v134
	v_exp_f32_e32 v134, v134
	s_nop 0
	v_add_f32_e32 v134, 1.0, v134
	v_rcp_f32_e32 v134, v134
	s_nop 0
	v_mul_f32_e32 v124, v124, v134
	v_mul_f32_e32 v134, 0x3d372713, v129
	v_mul_f32_e32 v134, v129, v134
	v_fma_f32 v134, v129, v134, v129
	v_mul_f32_e32 v134, 0x3f4c422a, v134
	v_mul_f32_e32 v134, 0xc038aa3b, v134
	v_exp_f32_e32 v134, v134
	s_nop 0
	v_add_f32_e32 v134, 1.0, v134
	v_rcp_f32_e32 v134, v134
	s_nop 0
	v_mul_f32_e32 v129, v129, v134
	v_mul_f32_e32 v134, 0x3d372713, v125
	v_mul_f32_e32 v134, v125, v134
	v_fma_f32 v134, v125, v134, v125
	v_mul_f32_e32 v134, 0x3f4c422a, v134
	v_mul_f32_e32 v134, 0xc038aa3b, v134
	v_exp_f32_e32 v134, v134
	s_nop 0
	v_add_f32_e32 v134, 1.0, v134
	v_rcp_f32_e32 v134, v134
	s_nop 0
	v_mul_f32_e32 v125, v125, v134
	v_cvt_pk_bf16_f32 v134, v126, v127
	v_cvt_pk_bf16_f32 v135, v128, v129
	v_cvt_pk_bf16_f32 v136, v122, v123
	v_cvt_pk_bf16_f32 v137, v124, v125
	s_nop 0
	v_readfirstlane_b32 s98, v132
	v_readfirstlane_b32 s99, v133
	ds_write_b128 v222, v[134:137]
	ds_read_b128 v[230:233], v223
	s_nop 1
	v_mul_f32_e32 v134, 0x3d372713, v118
	v_mul_f32_e32 v134, v118, v134
	v_fma_f32 v134, v118, v134, v118
	v_mul_f32_e32 v134, 0x3f4c422a, v134
	v_mul_f32_e32 v134, 0xc038aa3b, v134
	v_exp_f32_e32 v134, v134
	s_nop 0
	v_add_f32_e32 v134, 1.0, v134
	v_rcp_f32_e32 v134, v134
	s_nop 0
	v_mul_f32_e32 v118, v118, v134
	v_mul_f32_e32 v134, 0x3d372713, v114
	v_mul_f32_e32 v134, v114, v134
	v_fma_f32 v134, v114, v134, v114
	v_mul_f32_e32 v134, 0x3f4c422a, v134
	v_mul_f32_e32 v134, 0xc038aa3b, v134
	v_exp_f32_e32 v134, v134
	s_nop 0
	v_add_f32_e32 v134, 1.0, v134
	v_rcp_f32_e32 v134, v134
	s_nop 0
	v_mul_f32_e32 v114, v114, v134
	v_mul_f32_e32 v134, 0x3d372713, v119
	v_mul_f32_e32 v134, v119, v134
	v_fma_f32 v134, v119, v134, v119
	v_mul_f32_e32 v134, 0x3f4c422a, v134
	v_mul_f32_e32 v134, 0xc038aa3b, v134
	v_exp_f32_e32 v134, v134
	s_nop 0
	v_add_f32_e32 v134, 1.0, v134
	v_rcp_f32_e32 v134, v134
	s_nop 0
	v_mul_f32_e32 v119, v119, v134
	v_mul_f32_e32 v134, 0x3d372713, v115
	v_mul_f32_e32 v134, v115, v134
	v_fma_f32 v134, v115, v134, v115
	v_mul_f32_e32 v134, 0x3f4c422a, v134
	v_mul_f32_e32 v134, 0xc038aa3b, v134
	v_exp_f32_e32 v134, v134
	s_nop 0
	v_add_f32_e32 v134, 1.0, v134
	v_rcp_f32_e32 v134, v134
	s_nop 0
	v_mul_f32_e32 v115, v115, v134
	v_mul_f32_e32 v134, 0x3d372713, v120
	v_mul_f32_e32 v134, v120, v134
	v_fma_f32 v134, v120, v134, v120
	v_mul_f32_e32 v134, 0x3f4c422a, v134
	v_mul_f32_e32 v134, 0xc038aa3b, v134
	v_exp_f32_e32 v134, v134
	s_nop 0
	v_add_f32_e32 v134, 1.0, v134
	v_rcp_f32_e32 v134, v134
	s_nop 0
	v_mul_f32_e32 v120, v120, v134
	v_mul_f32_e32 v134, 0x3d372713, v116
	v_mul_f32_e32 v134, v116, v134
	v_fma_f32 v134, v116, v134, v116
	v_mul_f32_e32 v134, 0x3f4c422a, v134
	v_mul_f32_e32 v134, 0xc038aa3b, v134
	v_exp_f32_e32 v134, v134
	s_nop 0
	v_add_f32_e32 v134, 1.0, v134
	v_rcp_f32_e32 v134, v134
	s_nop 0
	v_mul_f32_e32 v116, v116, v134
	v_mul_f32_e32 v134, 0x3d372713, v121
	v_mul_f32_e32 v134, v121, v134
	v_fma_f32 v134, v121, v134, v121
	v_mul_f32_e32 v134, 0x3f4c422a, v134
	v_mul_f32_e32 v134, 0xc038aa3b, v134
	v_exp_f32_e32 v134, v134
	s_nop 0
	v_add_f32_e32 v134, 1.0, v134
	v_rcp_f32_e32 v134, v134
	s_nop 0
	v_mul_f32_e32 v121, v121, v134
	v_mul_f32_e32 v134, 0x3d372713, v117
	v_mul_f32_e32 v134, v117, v134
	v_fma_f32 v134, v117, v134, v117
	v_mul_f32_e32 v134, 0x3f4c422a, v134
	v_mul_f32_e32 v134, 0xc038aa3b, v134
	v_exp_f32_e32 v134, v134
	s_nop 0
	v_add_f32_e32 v134, 1.0, v134
	v_rcp_f32_e32 v134, v134
	s_nop 0
	v_mul_f32_e32 v117, v117, v134
	v_cvt_pk_bf16_f32 v134, v118, v119
	v_cvt_pk_bf16_f32 v135, v120, v121
	v_cvt_pk_bf16_f32 v136, v114, v115
	v_cvt_pk_bf16_f32 v137, v116, v117
	s_waitcnt lgkmcnt(0)
	global_store_dwordx4 v224, v[230:233], s[98:99]
	s_nop 0
	v_readfirstlane_b32 s98, v132
	v_readfirstlane_b32 s99, v133
	ds_write_b128 v222, v[134:137]
	ds_read_b128 v[230:233], v223
	s_cbranch_vccnz .LBB0_218
; __device__ __forceinline__ unsigned cvt_pk_bf16(float lo, float hi) { unsigned r; asm volatile("v_cvt_pk_bf16_f32 %0, %1, %2" : "=v"(r) : "v"(lo), "v"(hi)); return r; }
; __device__ __forceinline__ float quad_sum(float s) { s += __shfl_xor(s, 16); s += __shfl_xor(s, 32); return s; }
;     __device__ __forceinline__ void operator()(const f32x4 (&acc)[2][2][4][2], const Unit& u, int wr, int wc, int fr, int fq) const {
;     ...
;                         s1 += (v0[0] + v0[1]) + (v0[2] + v0[3]) + (v1[0] + v1[1]) + (v1[2] + v1[3]);
;                         s2 += (v0[0] * v0[0] + v0[1] * v0[1]) + (v0[2] * v0[2] + v0[3] * v0[3]) + (v1[0] * v1[0] + v1[1] * v1[1]) + (v1[2] * v1[2] + v1[3] * v1[3]);
;                         u32x4 w; w.x = cvt_pk_bf16(v0[0], v0[1]); w.y = cvt_pk_bf16(v0[2], v0[3]); w.z = cvt_pk_bf16(v1[0], v1[1]); w.w = cvt_pk_bf16(v1[2], v1[3]);
;                         *(u32x4*)(rowp + bj * HALF) = w; }
;                     if (stats) { s1 = quad_sum(s1); s2 = quad_sum(s2); if (fq == 0) { atomicAdd(st1 + row, s1); atomicAdd(st2 + row, s2); } } }
	s_nop 0
	v_mul_f32_e32 v134, v127, v127
	v_mul_f32_e32 v135, v129, v129
	v_mul_f32_e32 v133, v123, v123
	v_fmac_f32_e32 v134, v126, v126
	v_fmac_f32_e32 v135, v128, v128
	v_mul_f32_e32 v132, v125, v125
	v_fmac_f32_e32 v133, v122, v122
	v_add_f32_e32 v134, v134, v135
	v_fmac_f32_e32 v132, v124, v124
	v_add_f32_e32 v133, v134, v133
	v_add_f32_e32 v132, v132, v133
	v_mul_f32_e32 v133, v117, v117
	v_mul_f32_e32 v134, v115, v115
	v_fmac_f32_e32 v133, v116, v116
	v_fmac_f32_e32 v134, v114, v114
	v_add_f32_e32 v116, v116, v117
	v_add_f32_e32 v114, v114, v115
	v_add_f32_e32 v115, v118, v119
	v_add_f32_e32 v117, v120, v121
	v_add_f32_e32 v115, v115, v117
	v_add_f32_e32 v124, v124, v125
	v_add_f32_e32 v122, v122, v123
	v_add_f32_e32 v123, v126, v127
	v_add_f32_e32 v125, v128, v129
	v_add_f32_e32 v114, v115, v114
	v_add_f32_e32 v123, v123, v125
	v_add_f32_e32 v114, v116, v114
	v_and_b32_e32 v116, 64, v183
	v_add_f32_e32 v122, v123, v122
	v_xor_b32_e32 v115, 16, v183
	v_add_u32_e32 v116, 64, v116
	v_mul_f32_e32 v135, v119, v119
	v_mul_f32_e32 v136, v121, v121
	v_add_f32_e32 v122, v124, v122
	v_cmp_lt_i32_e32 vcc, v115, v116
	v_fmac_f32_e32 v135, v118, v118
	v_fmac_f32_e32 v136, v120, v120
	v_add_f32_e32 v122, 0, v122
	v_cndmask_b32_e32 v115, v183, v115, vcc
	v_add_f32_e32 v114, v122, v114
	v_lshlrev_b32_e32 v115, 2, v115
	v_add_f32_e32 v118, v135, v136
	ds_bpermute_b32 v117, v115, v114
	v_add_f32_e32 v118, v118, v134
	v_add_f32_e32 v118, v133, v118
	v_add_f32_e32 v118, v132, v118
	ds_bpermute_b32 v119, v115, v118
	s_waitcnt lgkmcnt(0)
	v_add_f32_e32 v114, v114, v117
	v_xor_b32_e32 v117, 32, v183
	v_cmp_lt_i32_e32 vcc, v117, v116
	v_add_f32_e32 v116, v118, v119
	s_nop 0
	v_cndmask_b32_e32 v115, v183, v117, vcc
	v_lshlrev_b32_e32 v117, 2, v115
	ds_bpermute_b32 v115, v117, v114
	ds_bpermute_b32 v117, v117, v116
	s_and_saveexec_b64 s[6:7], s[2:3]
	s_cbranch_execz .LBB0_217
	v_lshlrev_b64 v[118:119], 2, v[166:167]
	v_lshl_add_u64 v[120:121], s[78:79], 0, v[118:119]
	v_lshl_add_u64 v[118:119], s[76:77], 0, v[118:119]
	s_waitcnt lgkmcnt(0)
	v_add_f32_e32 v114, v114, v115
	v_add_f32_e32 v116, v116, v117
	global_atomic_add_f32 v[118:119], v114, off
	global_atomic_add_f32 v[120:121], v116, off

; __device__ __forceinline__ unsigned cvt_pk_bf16(float lo, float hi) { unsigned r; asm volatile("v_cvt_pk_bf16_f32 %0, %1, %2" : "=v"(r) : "v"(lo), "v"(hi)); return r; }
; __device__ __forceinline__ float gelu_t(float x) { const float u = 0.7978845608028654f * (x + 0.044715f * x * x * x); return x * fast_rcp(1.0f + fast_exp2(-2.8853900817779268f * u)); }
;     __device__ __forceinline__ void operator()(const f32x4 (&acc)[2][2][4][2], const Unit& u, int wr, int wc, int fr, int fq) const {
;     ...
;                 for (int m = 0; m < 4; ++m) { const int row = row0 + ai * HALF + m * 16; bf16_t* rowp = dst + (size_t)row * 512 + col0; float s1 = 0.f, s2 = 0.f;
; #pragma unroll
;                     for (int bj = 0; bj < 2; ++bj) { f32x4 v0 = acc[ai][bj][m][0], v1 = acc[ai][bj][m][1];
; #pragma unroll
;                         for (int j = 0; j < 4; ++j) { v0[j] = gelu_t(v0[j]); v1[j] = gelu_t(v1[j]); }
;                         s1 += (v0[0] + v0[1]) + (v0[2] + v0[3]) + (v1[0] + v1[1]) + (v1[2] + v1[3]);
;                         s2 += (v0[0] * v0[0] + v0[1] * v0[1]) + (v0[2] * v0[2] + v0[3] * v0[3]) + (v1[0] * v1[0] + v1[1] * v1[1]) + (v1[2] * v1[2] + v1[3] * v1[3]);
;                         u32x4 w; w.x = cvt_pk_bf16(v0[0], v0[1]); w.y = cvt_pk_bf16(v0[2], v0[3]); w.z = cvt_pk_bf16(v1[0], v1[1]); w.w = cvt_pk_bf16(v1[2], v1[3]);
;                         *(u32x4*)(rowp + bj * HALF) = w; }
.LBB0_218:
	v_mul_f32_e32 v118, 0x3d372713, v110
	v_mul_f32_e32 v118, v110, v118
	v_fma_f32 v118, v110, v118, v110
	v_mul_f32_e32 v118, 0x3f4c422a, v118
	v_mul_f32_e32 v118, 0xc038aa3b, v118
	v_exp_f32_e32 v118, v118
	v_or_b32_e32 v114, 16, v166
	s_waitcnt lgkmcnt(0)
	v_ashrrev_i32_e32 v115, 31, v114
	v_lshlrev_b64 v[116:117], 10, v[114:115]
	v_add_f32_e32 v118, 1.0, v118
	v_rcp_f32_e32 v118, v118
	v_lshl_add_u64 v[116:117], v[130:131], 0, v[116:117]
	s_andn2_b64 vcc, exec, s[8:9]
	v_mul_f32_e32 v110, v110, v118
	v_mul_f32_e32 v118, 0x3d372713, v106
	v_mul_f32_e32 v118, v106, v118
	v_fma_f32 v118, v106, v118, v106
	v_mul_f32_e32 v118, 0x3f4c422a, v118
	v_mul_f32_e32 v118, 0xc038aa3b, v118
	v_exp_f32_e32 v118, v118
	s_nop 0
	v_add_f32_e32 v118, 1.0, v118
	v_rcp_f32_e32 v118, v118
	s_nop 0
	v_mul_f32_e32 v106, v106, v118
	v_mul_f32_e32 v118, 0x3d372713, v111
	v_mul_f32_e32 v118, v111, v118
	v_fma_f32 v118, v111, v118, v111
	v_mul_f32_e32 v118, 0x3f4c422a, v118
	v_mul_f32_e32 v118, 0xc038aa3b, v118
	v_exp_f32_e32 v118, v118
	s_nop 0
	v_add_f32_e32 v118, 1.0, v118
	v_rcp_f32_e32 v118, v118
	s_nop 0
	v_mul_f32_e32 v111, v111, v118
	v_mul_f32_e32 v118, 0x3d372713, v107
	v_mul_f32_e32 v118, v107, v118
	v_fma_f32 v118, v107, v118, v107
	v_mul_f32_e32 v118, 0x3f4c422a, v118
	v_mul_f32_e32 v118, 0xc038aa3b, v118
	v_exp_f32_e32 v118, v118
	s_nop 0
	v_add_f32_e32 v118, 1.0, v118
	v_rcp_f32_e32 v118, v118
	s_nop 0
	v_mul_f32_e32 v107, v107, v118
	v_mul_f32_e32 v118, 0x3d372713, v112
	v_mul_f32_e32 v118, v112, v118
	v_fma_f32 v118, v112, v118, v112
	v_mul_f32_e32 v118, 0x3f4c422a, v118
	v_mul_f32_e32 v118, 0xc038aa3b, v118
	v_exp_f32_e32 v118, v118
	s_nop 0
	v_add_f32_e32 v118, 1.0, v118
	v_rcp_f32_e32 v118, v118
	s_nop 0
	v_mul_f32_e32 v112, v112, v118
	v_mul_f32_e32 v118, 0x3d372713, v108
	v_mul_f32_e32 v118, v108, v118
	v_fma_f32 v118, v108, v118, v108
	v_mul_f32_e32 v118, 0x3f4c422a, v118
	v_mul_f32_e32 v118, 0xc038aa3b, v118
	v_exp_f32_e32 v118, v118
	s_nop 0
	v_add_f32_e32 v118, 1.0, v118
	v_rcp_f32_e32 v118, v118
	s_nop 0
	v_mul_f32_e32 v108, v108, v118
	v_mul_f32_e32 v118, 0x3d372713, v113
	v_mul_f32_e32 v118, v113, v118
	v_fma_f32 v118, v113, v118, v113
	v_mul_f32_e32 v118, 0x3f4c422a, v118
	v_mul_f32_e32 v118, 0xc038aa3b, v118
	v_exp_f32_e32 v118, v118
	s_nop 0
	v_add_f32_e32 v118, 1.0, v118
	v_rcp_f32_e32 v118, v118
	s_nop 0
	v_mul_f32_e32 v113, v113, v118
	v_mul_f32_e32 v118, 0x3d372713, v109
	v_mul_f32_e32 v118, v109, v118
	v_fma_f32 v118, v109, v118, v109
	v_mul_f32_e32 v118, 0x3f4c422a, v118
	v_mul_f32_e32 v118, 0xc038aa3b, v118
	v_exp_f32_e32 v118, v118
	s_nop 0
	v_add_f32_e32 v118, 1.0, v118
	v_rcp_f32_e32 v118, v118
	s_nop 0
	v_mul_f32_e32 v109, v109, v118
	v_cvt_pk_bf16_f32 v118, v110, v111
	v_cvt_pk_bf16_f32 v119, v112, v113
	v_cvt_pk_bf16_f32 v120, v106, v107
	v_cvt_pk_bf16_f32 v121, v108, v109
	s_waitcnt lgkmcnt(0)
	global_store_dwordx4 v224, v[230:233], s[98:99] offset:256
	s_nop 0
	v_readfirstlane_b32 s98, v116
	v_readfirstlane_b32 s99, v117
	ds_write_b128 v222, v[118:121]
	ds_read_b128 v[230:233], v223
	s_nop 1
	v_mul_f32_e32 v118, 0x3d372713, v102
	v_mul_f32_e32 v118, v102, v118
	v_fma_f32 v118, v102, v118, v102
	v_mul_f32_e32 v118, 0x3f4c422a, v118
	v_mul_f32_e32 v118, 0xc038aa3b, v118
	v_exp_f32_e32 v118, v118
	s_nop 0
	v_add_f32_e32 v118, 1.0, v118
	v_rcp_f32_e32 v118, v118
	s_nop 0
	v_mul_f32_e32 v102, v102, v118
	v_mul_f32_e32 v118, 0x3d372713, v98
	v_mul_f32_e32 v118, v98, v118
	v_fma_f32 v118, v98, v118, v98
	v_mul_f32_e32 v118, 0x3f4c422a, v118
	v_mul_f32_e32 v118, 0xc038aa3b, v118
	v_exp_f32_e32 v118, v118
	s_nop 0
	v_add_f32_e32 v118, 1.0, v118
	v_rcp_f32_e32 v118, v118
	s_nop 0
	v_mul_f32_e32 v98, v98, v118
	v_mul_f32_e32 v118, 0x3d372713, v103
	v_mul_f32_e32 v118, v103, v118
	v_fma_f32 v118, v103, v118, v103
	v_mul_f32_e32 v118, 0x3f4c422a, v118
	v_mul_f32_e32 v118, 0xc038aa3b, v118
	v_exp_f32_e32 v118, v118
	s_nop 0
	v_add_f32_e32 v118, 1.0, v118
	v_rcp_f32_e32 v118, v118
	s_nop 0
	v_mul_f32_e32 v103, v103, v118
	v_mul_f32_e32 v118, 0x3d372713, v99
	v_mul_f32_e32 v118, v99, v118
	v_fma_f32 v118, v99, v118, v99
	v_mul_f32_e32 v118, 0x3f4c422a, v118
	v_mul_f32_e32 v118, 0xc038aa3b, v118
	v_exp_f32_e32 v118, v118
	s_nop 0
	v_add_f32_e32 v118, 1.0, v118
	v_rcp_f32_e32 v118, v118
	s_nop 0
	v_mul_f32_e32 v99, v99, v118
	v_mul_f32_e32 v118, 0x3d372713, v104
	v_mul_f32_e32 v118, v104, v118
	v_fma_f32 v118, v104, v118, v104
	v_mul_f32_e32 v118, 0x3f4c422a, v118
	v_mul_f32_e32 v118, 0xc038aa3b, v118
	v_exp_f32_e32 v118, v118
	s_nop 0
	v_add_f32_e32 v118, 1.0, v118
	v_rcp_f32_e32 v118, v118
	s_nop 0
	v_mul_f32_e32 v104, v104, v118
	v_mul_f32_e32 v118, 0x3d372713, v100
	v_mul_f32_e32 v118, v100, v118
	v_fma_f32 v118, v100, v118, v100
	v_mul_f32_e32 v118, 0x3f4c422a, v118
	v_mul_f32_e32 v118, 0xc038aa3b, v118
	v_exp_f32_e32 v118, v118
	s_nop 0
	v_add_f32_e32 v118, 1.0, v118
	v_rcp_f32_e32 v118, v118
	s_nop 0
	v_mul_f32_e32 v100, v100, v118
	v_mul_f32_e32 v118, 0x3d372713, v105
	v_mul_f32_e32 v118, v105, v118
	v_fma_f32 v118, v105, v118, v105
	v_mul_f32_e32 v118, 0x3f4c422a, v118
	v_mul_f32_e32 v118, 0xc038aa3b, v118
	v_exp_f32_e32 v118, v118
	s_nop 0
	v_add_f32_e32 v118, 1.0, v118
	v_rcp_f32_e32 v118, v118
	s_nop 0
	v_mul_f32_e32 v105, v105, v118
	v_mul_f32_e32 v118, 0x3d372713, v101
	v_mul_f32_e32 v118, v101, v118
	v_fma_f32 v118, v101, v118, v101
	v_mul_f32_e32 v118, 0x3f4c422a, v118
	v_mul_f32_e32 v118, 0xc038aa3b, v118
	v_exp_f32_e32 v118, v118
	s_nop 0
	v_add_f32_e32 v118, 1.0, v118
	v_rcp_f32_e32 v118, v118
	s_nop 0
	v_mul_f32_e32 v101, v101, v118
	v_cvt_pk_bf16_f32 v118, v102, v103
	v_cvt_pk_bf16_f32 v119, v104, v105
	v_cvt_pk_bf16_f32 v120, v98, v99
	v_cvt_pk_bf16_f32 v121, v100, v101
	s_waitcnt lgkmcnt(0)
	global_store_dwordx4 v224, v[230:233], s[98:99]
	s_nop 0
	v_readfirstlane_b32 s98, v116
	v_readfirstlane_b32 s99, v117
	ds_write_b128 v222, v[118:121]
	ds_read_b128 v[230:233], v223
	v_cndmask_b32_e64 v116, 0, 1, s[8:9]
	v_cmp_ne_u32_e64 s[6:7], 1, v116
	s_cbranch_vccnz .LBB0_222
; __device__ __forceinline__ unsigned cvt_pk_bf16(float lo, float hi) { unsigned r; asm volatile("v_cvt_pk_bf16_f32 %0, %1, %2" : "=v"(r) : "v"(lo), "v"(hi)); return r; }
; __device__ __forceinline__ float quad_sum(float s) { s += __shfl_xor(s, 16); s += __shfl_xor(s, 32); return s; }
;     __device__ __forceinline__ void operator()(const f32x4 (&acc)[2][2][4][2], const Unit& u, int wr, int wc, int fr, int fq) const {
;     ...
;                         s1 += (v0[0] + v0[1]) + (v0[2] + v0[3]) + (v1[0] + v1[1]) + (v1[2] + v1[3]);
;                         s2 += (v0[0] * v0[0] + v0[1] * v0[1]) + (v0[2] * v0[2] + v0[3] * v0[3]) + (v1[0] * v1[0] + v1[1] * v1[1]) + (v1[2] * v1[2] + v1[3] * v1[3]);
;                         u32x4 w; w.x = cvt_pk_bf16(v0[0], v0[1]); w.y = cvt_pk_bf16(v0[2], v0[3]); w.z = cvt_pk_bf16(v1[0], v1[1]); w.w = cvt_pk_bf16(v1[2], v1[3]);
;                         *(u32x4*)(rowp + bj * HALF) = w; }
;                     if (stats) { s1 = quad_sum(s1); s2 = quad_sum(s2); if (fq == 0) { atomicAdd(st1 + row, s1); atomicAdd(st2 + row, s2); } } }
	v_mul_f32_e32 v118, v111, v111
	v_mul_f32_e32 v119, v113, v113
	v_mul_f32_e32 v117, v107, v107
	v_fmac_f32_e32 v118, v110, v110
	v_fmac_f32_e32 v119, v112, v112
	v_mul_f32_e32 v116, v109, v109
	v_fmac_f32_e32 v117, v106, v106
	v_add_f32_e32 v118, v118, v119
	v_fmac_f32_e32 v116, v108, v108
	v_add_f32_e32 v117, v118, v117
	v_add_f32_e32 v116, v116, v117
	v_mul_f32_e32 v117, v101, v101
	v_mul_f32_e32 v118, v99, v99
	v_fmac_f32_e32 v117, v100, v100
	v_fmac_f32_e32 v118, v98, v98
	v_add_f32_e32 v100, v100, v101
	v_add_f32_e32 v98, v98, v99
	v_add_f32_e32 v99, v102, v103
	v_add_f32_e32 v101, v104, v105
	v_add_f32_e32 v99, v99, v101
	v_add_f32_e32 v108, v108, v109
	v_add_f32_e32 v106, v106, v107
	v_add_f32_e32 v107, v110, v111
	v_add_f32_e32 v109, v112, v113
	v_add_f32_e32 v98, v99, v98
	v_add_f32_e32 v107, v107, v109
	v_add_f32_e32 v98, v100, v98
	v_and_b32_e32 v100, 64, v183
	v_add_f32_e32 v106, v107, v106
	v_xor_b32_e32 v99, 16, v183
	v_add_u32_e32 v100, 64, v100
	v_mul_f32_e32 v119, v103, v103
	v_mul_f32_e32 v120, v105, v105
	v_add_f32_e32 v106, v108, v106
	v_cmp_lt_i32_e32 vcc, v99, v100
	v_fmac_f32_e32 v119, v102, v102
	v_fmac_f32_e32 v120, v104, v104
	v_add_f32_e32 v106, 0, v106
	v_cndmask_b32_e32 v99, v183, v99, vcc
	v_add_f32_e32 v98, v106, v98
	v_lshlrev_b32_e32 v99, 2, v99
	v_add_f32_e32 v102, v119, v120
	ds_bpermute_b32 v101, v99, v98
	v_add_f32_e32 v102, v102, v118
	v_add_f32_e32 v102, v117, v102
	v_add_f32_e32 v102, v116, v102
	ds_bpermute_b32 v103, v99, v102
	s_waitcnt lgkmcnt(0)
	v_add_f32_e32 v98, v98, v101
	v_xor_b32_e32 v101, 32, v183
	v_cmp_lt_i32_e32 vcc, v101, v100
	v_add_f32_e32 v100, v102, v103
	s_nop 0
	v_cndmask_b32_e32 v99, v183, v101, vcc
	v_lshlrev_b32_e32 v101, 2, v99
	ds_bpermute_b32 v99, v101, v98
	ds_bpermute_b32 v101, v101, v100
	s_and_saveexec_b64 s[8:9], s[2:3]
	s_cbranch_execz .LBB0_221
	v_lshlrev_b64 v[102:103], 2, v[114:115]
	v_lshl_add_u64 v[104:105], s[78:79], 0, v[102:103]
	v_lshl_add_u64 v[102:103], s[76:77], 0, v[102:103]
	s_waitcnt lgkmcnt(0)
	v_add_f32_e32 v98, v98, v99
	v_add_f32_e32 v100, v100, v101
	global_atomic_add_f32 v[102:103], v98, off
	global_atomic_add_f32 v[104:105], v100, off

; __device__ __forceinline__ unsigned cvt_pk_bf16(float lo, float hi) { unsigned r; asm volatile("v_cvt_pk_bf16_f32 %0, %1, %2" : "=v"(r) : "v"(lo), "v"(hi)); return r; }
; __device__ __forceinline__ float gelu_t(float x) { const float u = 0.7978845608028654f * (x + 0.044715f * x * x * x); return x * fast_rcp(1.0f + fast_exp2(-2.8853900817779268f * u)); }
;     __device__ __forceinline__ void operator()(const f32x4 (&acc)[2][2][4][2], const Unit& u, int wr, int wc, int fr, int fq) const {
;     ...
;                 for (int m = 0; m < 4; ++m) { const int row = row0 + ai * HALF + m * 16; bf16_t* rowp = dst + (size_t)row * 512 + col0; float s1 = 0.f, s2 = 0.f;
; #pragma unroll
;                     for (int bj = 0; bj < 2; ++bj) { f32x4 v0 = acc[ai][bj][m][0], v1 = acc[ai][bj][m][1];
; #pragma unroll
;                         for (int j = 0; j < 4; ++j) { v0[j] = gelu_t(v0[j]); v1[j] = gelu_t(v1[j]); }
;                         s1 += (v0[0] + v0[1]) + (v0[2] + v0[3]) + (v1[0] + v1[1]) + (v1[2] + v1[3]);
;                         s2 += (v0[0] * v0[0] + v0[1] * v0[1]) + (v0[2] * v0[2] + v0[3] * v0[3]) + (v1[0] * v1[0] + v1[1] * v1[1]) + (v1[2] * v1[2] + v1[3] * v1[3]);
;                         u32x4 w; w.x = cvt_pk_bf16(v0[0], v0[1]); w.y = cvt_pk_bf16(v0[2], v0[3]); w.z = cvt_pk_bf16(v1[0], v1[1]); w.w = cvt_pk_bf16(v1[2], v1[3]);
;                         *(u32x4*)(rowp + bj * HALF) = w; }
.LBB0_222:
	v_mul_f32_e32 v102, 0x3d372713, v94
	v_mul_f32_e32 v102, v94, v102
	v_fma_f32 v102, v94, v102, v94
	v_mul_f32_e32 v102, 0x3f4c422a, v102
	v_mul_f32_e32 v102, 0xc038aa3b, v102
	v_exp_f32_e32 v102, v102
	v_or_b32_e32 v98, 32, v166
	s_waitcnt lgkmcnt(0)
	v_ashrrev_i32_e32 v99, 31, v98
	v_lshlrev_b64 v[100:101], 10, v[98:99]
	v_add_f32_e32 v102, 1.0, v102
	v_rcp_f32_e32 v102, v102
	v_lshl_add_u64 v[100:101], v[130:131], 0, v[100:101]
	s_and_b64 vcc, exec, s[6:7]
	v_mul_f32_e32 v94, v94, v102
	v_mul_f32_e32 v102, 0x3d372713, v90
	v_mul_f32_e32 v102, v90, v102
	v_fma_f32 v102, v90, v102, v90
	v_mul_f32_e32 v102, 0x3f4c422a, v102
	v_mul_f32_e32 v102, 0xc038aa3b, v102
	v_exp_f32_e32 v102, v102
	s_nop 0
	v_add_f32_e32 v102, 1.0, v102
	v_rcp_f32_e32 v102, v102
	s_nop 0
	v_mul_f32_e32 v90, v90, v102
	v_mul_f32_e32 v102, 0x3d372713, v95
	v_mul_f32_e32 v102, v95, v102
	v_fma_f32 v102, v95, v102, v95
	v_mul_f32_e32 v102, 0x3f4c422a, v102
	v_mul_f32_e32 v102, 0xc038aa3b, v102
	v_exp_f32_e32 v102, v102
	s_nop 0
	v_add_f32_e32 v102, 1.0, v102
	v_rcp_f32_e32 v102, v102
	s_nop 0
	v_mul_f32_e32 v95, v95, v102
	v_mul_f32_e32 v102, 0x3d372713, v91
	v_mul_f32_e32 v102, v91, v102
	v_fma_f32 v102, v91, v102, v91
	v_mul_f32_e32 v102, 0x3f4c422a, v102
	v_mul_f32_e32 v102, 0xc038aa3b, v102
	v_exp_f32_e32 v102, v102
	s_nop 0
	v_add_f32_e32 v102, 1.0, v102
	v_rcp_f32_e32 v102, v102
	s_nop 0
	v_mul_f32_e32 v91, v91, v102
	v_mul_f32_e32 v102, 0x3d372713, v96
	v_mul_f32_e32 v102, v96, v102
	v_fma_f32 v102, v96, v102, v96
	v_mul_f32_e32 v102, 0x3f4c422a, v102
	v_mul_f32_e32 v102, 0xc038aa3b, v102
	v_exp_f32_e32 v102, v102
	s_nop 0
	v_add_f32_e32 v102, 1.0, v102
	v_rcp_f32_e32 v102, v102
	s_nop 0
	v_mul_f32_e32 v96, v96, v102
	v_mul_f32_e32 v102, 0x3d372713, v92
	v_mul_f32_e32 v102, v92, v102
	v_fma_f32 v102, v92, v102, v92
	v_mul_f32_e32 v102, 0x3f4c422a, v102
	v_mul_f32_e32 v102, 0xc038aa3b, v102
	v_exp_f32_e32 v102, v102
	s_nop 0
	v_add_f32_e32 v102, 1.0, v102
	v_rcp_f32_e32 v102, v102
	s_nop 0
	v_mul_f32_e32 v92, v92, v102
	v_mul_f32_e32 v102, 0x3d372713, v97
	v_mul_f32_e32 v102, v97, v102
	v_fma_f32 v102, v97, v102, v97
	v_mul_f32_e32 v102, 0x3f4c422a, v102
	v_mul_f32_e32 v102, 0xc038aa3b, v102
	v_exp_f32_e32 v102, v102
	s_nop 0
	v_add_f32_e32 v102, 1.0, v102
	v_rcp_f32_e32 v102, v102
	s_nop 0
	v_mul_f32_e32 v97, v97, v102
	v_mul_f32_e32 v102, 0x3d372713, v93
	v_mul_f32_e32 v102, v93, v102
	v_fma_f32 v102, v93, v102, v93
	v_mul_f32_e32 v102, 0x3f4c422a, v102
	v_mul_f32_e32 v102, 0xc038aa3b, v102
	v_exp_f32_e32 v102, v102
	s_nop 0
	v_add_f32_e32 v102, 1.0, v102
	v_rcp_f32_e32 v102, v102
	s_nop 0
	v_mul_f32_e32 v93, v93, v102
	v_cvt_pk_bf16_f32 v102, v94, v95
	v_cvt_pk_bf16_f32 v103, v96, v97
	v_cvt_pk_bf16_f32 v104, v90, v91
	v_cvt_pk_bf16_f32 v105, v92, v93
	s_waitcnt lgkmcnt(0)
	global_store_dwordx4 v224, v[230:233], s[98:99] offset:256
	s_nop 0
	v_readfirstlane_b32 s98, v100
	v_readfirstlane_b32 s99, v101
	ds_write_b128 v222, v[102:105]
	ds_read_b128 v[230:233], v223
	s_nop 1
	v_mul_f32_e32 v102, 0x3d372713, v86
	v_mul_f32_e32 v102, v86, v102
	v_fma_f32 v102, v86, v102, v86
	v_mul_f32_e32 v102, 0x3f4c422a, v102
	v_mul_f32_e32 v102, 0xc038aa3b, v102
	v_exp_f32_e32 v102, v102
	s_nop 0
	v_add_f32_e32 v102, 1.0, v102
	v_rcp_f32_e32 v102, v102
	s_nop 0
	v_mul_f32_e32 v86, v86, v102
	v_mul_f32_e32 v102, 0x3d372713, v82
	v_mul_f32_e32 v102, v82, v102
	v_fma_f32 v102, v82, v102, v82
	v_mul_f32_e32 v102, 0x3f4c422a, v102
	v_mul_f32_e32 v102, 0xc038aa3b, v102
	v_exp_f32_e32 v102, v102
	s_nop 0
	v_add_f32_e32 v102, 1.0, v102
	v_rcp_f32_e32 v102, v102
	s_nop 0
	v_mul_f32_e32 v82, v82, v102
	v_mul_f32_e32 v102, 0x3d372713, v87
	v_mul_f32_e32 v102, v87, v102
	v_fma_f32 v102, v87, v102, v87
	v_mul_f32_e32 v102, 0x3f4c422a, v102
	v_mul_f32_e32 v102, 0xc038aa3b, v102
	v_exp_f32_e32 v102, v102
	s_nop 0
	v_add_f32_e32 v102, 1.0, v102
	v_rcp_f32_e32 v102, v102
	s_nop 0
	v_mul_f32_e32 v87, v87, v102
	v_mul_f32_e32 v102, 0x3d372713, v83
	v_mul_f32_e32 v102, v83, v102
	v_fma_f32 v102, v83, v102, v83
	v_mul_f32_e32 v102, 0x3f4c422a, v102
	v_mul_f32_e32 v102, 0xc038aa3b, v102
	v_exp_f32_e32 v102, v102
	s_nop 0
	v_add_f32_e32 v102, 1.0, v102
	v_rcp_f32_e32 v102, v102
	s_nop 0
	v_mul_f32_e32 v83, v83, v102
	v_mul_f32_e32 v102, 0x3d372713, v88
	v_mul_f32_e32 v102, v88, v102
	v_fma_f32 v102, v88, v102, v88
	v_mul_f32_e32 v102, 0x3f4c422a, v102
	v_mul_f32_e32 v102, 0xc038aa3b, v102
	v_exp_f32_e32 v102, v102
	s_nop 0
	v_add_f32_e32 v102, 1.0, v102
	v_rcp_f32_e32 v102, v102
	s_nop 0
	v_mul_f32_e32 v88, v88, v102
	v_mul_f32_e32 v102, 0x3d372713, v84
	v_mul_f32_e32 v102, v84, v102
	v_fma_f32 v102, v84, v102, v84
	v_mul_f32_e32 v102, 0x3f4c422a, v102
	v_mul_f32_e32 v102, 0xc038aa3b, v102
	v_exp_f32_e32 v102, v102
	s_nop 0
	v_add_f32_e32 v102, 1.0, v102
	v_rcp_f32_e32 v102, v102
	s_nop 0
	v_mul_f32_e32 v84, v84, v102
	v_mul_f32_e32 v102, 0x3d372713, v89
	v_mul_f32_e32 v102, v89, v102
	v_fma_f32 v102, v89, v102, v89
	v_mul_f32_e32 v102, 0x3f4c422a, v102
	v_mul_f32_e32 v102, 0xc038aa3b, v102
	v_exp_f32_e32 v102, v102
	s_nop 0
	v_add_f32_e32 v102, 1.0, v102
	v_rcp_f32_e32 v102, v102
	s_nop 0
	v_mul_f32_e32 v89, v89, v102
	v_mul_f32_e32 v102, 0x3d372713, v85
	v_mul_f32_e32 v102, v85, v102
	v_fma_f32 v102, v85, v102, v85
	v_mul_f32_e32 v102, 0x3f4c422a, v102
	v_mul_f32_e32 v102, 0xc038aa3b, v102
	v_exp_f32_e32 v102, v102
	s_nop 0
	v_add_f32_e32 v102, 1.0, v102
	v_rcp_f32_e32 v102, v102
	s_nop 0
	v_mul_f32_e32 v85, v85, v102
	v_cvt_pk_bf16_f32 v102, v86, v87
	v_cvt_pk_bf16_f32 v103, v88, v89
	v_cvt_pk_bf16_f32 v104, v82, v83
	v_cvt_pk_bf16_f32 v105, v84, v85
	s_waitcnt lgkmcnt(0)
	global_store_dwordx4 v224, v[230:233], s[98:99]
	s_nop 0
	v_readfirstlane_b32 s98, v100
	v_readfirstlane_b32 s99, v101
	ds_write_b128 v222, v[102:105]
	ds_read_b128 v[230:233], v223
	s_cbranch_vccnz .LBB0_226
; __device__ __forceinline__ unsigned cvt_pk_bf16(float lo, float hi) { unsigned r; asm volatile("v_cvt_pk_bf16_f32 %0, %1, %2" : "=v"(r) : "v"(lo), "v"(hi)); return r; }
; __device__ __forceinline__ float quad_sum(float s) { s += __shfl_xor(s, 16); s += __shfl_xor(s, 32); return s; }
;     __device__ __forceinline__ void operator()(const f32x4 (&acc)[2][2][4][2], const Unit& u, int wr, int wc, int fr, int fq) const {
;     ...
;                         s1 += (v0[0] + v0[1]) + (v0[2] + v0[3]) + (v1[0] + v1[1]) + (v1[2] + v1[3]);
;                         s2 += (v0[0] * v0[0] + v0[1] * v0[1]) + (v0[2] * v0[2] + v0[3] * v0[3]) + (v1[0] * v1[0] + v1[1] * v1[1]) + (v1[2] * v1[2] + v1[3] * v1[3]);
;                         u32x4 w; w.x = cvt_pk_bf16(v0[0], v0[1]); w.y = cvt_pk_bf16(v0[2], v0[3]); w.z = cvt_pk_bf16(v1[0], v1[1]); w.w = cvt_pk_bf16(v1[2], v1[3]);
;                         *(u32x4*)(rowp + bj * HALF) = w; }
;                     if (stats) { s1 = quad_sum(s1); s2 = quad_sum(s2); if (fq == 0) { atomicAdd(st1 + row, s1); atomicAdd(st2 + row, s2); } } }
	s_nop 0
	v_mul_f32_e32 v102, v95, v95
	v_mul_f32_e32 v103, v97, v97
	v_mul_f32_e32 v101, v91, v91
	v_fmac_f32_e32 v102, v94, v94
	v_fmac_f32_e32 v103, v96, v96
	v_mul_f32_e32 v100, v93, v93
	v_fmac_f32_e32 v101, v90, v90
	v_add_f32_e32 v102, v102, v103
	v_fmac_f32_e32 v100, v92, v92
	v_add_f32_e32 v101, v102, v101
	v_add_f32_e32 v100, v100, v101
	v_mul_f32_e32 v101, v85, v85
	v_mul_f32_e32 v102, v83, v83
	v_fmac_f32_e32 v101, v84, v84
	v_fmac_f32_e32 v102, v82, v82
	v_add_f32_e32 v84, v84, v85
	v_add_f32_e32 v82, v82, v83
	v_add_f32_e32 v83, v86, v87
	v_add_f32_e32 v85, v88, v89
	v_add_f32_e32 v83, v83, v85
	v_add_f32_e32 v92, v92, v93
	v_add_f32_e32 v90, v90, v91
	v_add_f32_e32 v91, v94, v95
	v_add_f32_e32 v93, v96, v97
	v_add_f32_e32 v82, v83, v82
	v_add_f32_e32 v91, v91, v93
	v_add_f32_e32 v82, v84, v82
	v_and_b32_e32 v84, 64, v183
	v_add_f32_e32 v90, v91, v90
	v_xor_b32_e32 v83, 16, v183
	v_add_u32_e32 v84, 64, v84
	v_mul_f32_e32 v103, v87, v87
	v_mul_f32_e32 v104, v89, v89
	v_add_f32_e32 v90, v92, v90
	v_cmp_lt_i32_e32 vcc, v83, v84
	v_fmac_f32_e32 v103, v86, v86
	v_fmac_f32_e32 v104, v88, v88
	v_add_f32_e32 v90, 0, v90
	v_cndmask_b32_e32 v83, v183, v83, vcc
	v_add_f32_e32 v82, v90, v82
	v_lshlrev_b32_e32 v83, 2, v83
	v_add_f32_e32 v86, v103, v104
	ds_bpermute_b32 v85, v83, v82
	v_add_f32_e32 v86, v86, v102
	v_add_f32_e32 v86, v101, v86
	v_add_f32_e32 v86, v100, v86
	ds_bpermute_b32 v87, v83, v86
	s_waitcnt lgkmcnt(0)
	v_add_f32_e32 v82, v82, v85
	v_xor_b32_e32 v85, 32, v183
	v_cmp_lt_i32_e32 vcc, v85, v84
	v_add_f32_e32 v84, v86, v87
	s_nop 0
	v_cndmask_b32_e32 v83, v183, v85, vcc
	v_lshlrev_b32_e32 v85, 2, v83
	ds_bpermute_b32 v83, v85, v82
	ds_bpermute_b32 v85, v85, v84
	s_and_saveexec_b64 s[8:9], s[2:3]
	s_cbranch_execz .LBB0_225
	v_lshlrev_b64 v[86:87], 2, v[98:99]
	v_lshl_add_u64 v[88:89], s[78:79], 0, v[86:87]
	v_lshl_add_u64 v[86:87], s[76:77], 0, v[86:87]
	s_waitcnt lgkmcnt(0)
	v_add_f32_e32 v82, v82, v83
	v_add_f32_e32 v84, v84, v85
	global_atomic_add_f32 v[86:87], v82, off
	global_atomic_add_f32 v[88:89], v84, off

; __device__ __forceinline__ unsigned cvt_pk_bf16(float lo, float hi) { unsigned r; asm volatile("v_cvt_pk_bf16_f32 %0, %1, %2" : "=v"(r) : "v"(lo), "v"(hi)); return r; }
; __device__ __forceinline__ float gelu_t(float x) { const float u = 0.7978845608028654f * (x + 0.044715f * x * x * x); return x * fast_rcp(1.0f + fast_exp2(-2.8853900817779268f * u)); }
;     __device__ __forceinline__ void operator()(const f32x4 (&acc)[2][2][4][2], const Unit& u, int wr, int wc, int fr, int fq) const {
;     ...
;                 for (int m = 0; m < 4; ++m) { const int row = row0 + ai * HALF + m * 16; bf16_t* rowp = dst + (size_t)row * 512 + col0; float s1 = 0.f, s2 = 0.f;
; #pragma unroll
;                     for (int bj = 0; bj < 2; ++bj) { f32x4 v0 = acc[ai][bj][m][0], v1 = acc[ai][bj][m][1];
; #pragma unroll
;                         for (int j = 0; j < 4; ++j) { v0[j] = gelu_t(v0[j]); v1[j] = gelu_t(v1[j]); }
;                         s1 += (v0[0] + v0[1]) + (v0[2] + v0[3]) + (v1[0] + v1[1]) + (v1[2] + v1[3]);
;                         s2 += (v0[0] * v0[0] + v0[1] * v0[1]) + (v0[2] * v0[2] + v0[3] * v0[3]) + (v1[0] * v1[0] + v1[1] * v1[1]) + (v1[2] * v1[2] + v1[3] * v1[3]);
;                         u32x4 w; w.x = cvt_pk_bf16(v0[0], v0[1]); w.y = cvt_pk_bf16(v0[2], v0[3]); w.z = cvt_pk_bf16(v1[0], v1[1]); w.w = cvt_pk_bf16(v1[2], v1[3]);
;                         *(u32x4*)(rowp + bj * HALF) = w; }
.LBB0_226:
	v_mul_f32_e32 v86, 0x3d372713, v78
	v_mul_f32_e32 v86, v78, v86
	v_fma_f32 v86, v78, v86, v78
	v_mul_f32_e32 v86, 0x3f4c422a, v86
	v_mul_f32_e32 v86, 0xc038aa3b, v86
	v_exp_f32_e32 v86, v86
	v_or_b32_e32 v82, 48, v166
	s_waitcnt lgkmcnt(0)
	v_ashrrev_i32_e32 v83, 31, v82
	v_lshlrev_b64 v[84:85], 10, v[82:83]
	v_add_f32_e32 v86, 1.0, v86
	v_rcp_f32_e32 v86, v86
	v_lshl_add_u64 v[84:85], v[130:131], 0, v[84:85]
	s_and_b64 vcc, exec, s[6:7]
	v_mul_f32_e32 v78, v78, v86
	v_mul_f32_e32 v86, 0x3d372713, v74
	v_mul_f32_e32 v86, v74, v86
	v_fma_f32 v86, v74, v86, v74
	v_mul_f32_e32 v86, 0x3f4c422a, v86
	v_mul_f32_e32 v86, 0xc038aa3b, v86
	v_exp_f32_e32 v86, v86
	s_nop 0
	v_add_f32_e32 v86, 1.0, v86
	v_rcp_f32_e32 v86, v86
	s_nop 0
	v_mul_f32_e32 v74, v74, v86
	v_mul_f32_e32 v86, 0x3d372713, v79
	v_mul_f32_e32 v86, v79, v86
	v_fma_f32 v86, v79, v86, v79
	v_mul_f32_e32 v86, 0x3f4c422a, v86
	v_mul_f32_e32 v86, 0xc038aa3b, v86
	v_exp_f32_e32 v86, v86
	s_nop 0
	v_add_f32_e32 v86, 1.0, v86
	v_rcp_f32_e32 v86, v86
	s_nop 0
	v_mul_f32_e32 v79, v79, v86
	v_mul_f32_e32 v86, 0x3d372713, v75
	v_mul_f32_e32 v86, v75, v86
	v_fma_f32 v86, v75, v86, v75
	v_mul_f32_e32 v86, 0x3f4c422a, v86
	v_mul_f32_e32 v86, 0xc038aa3b, v86
	v_exp_f32_e32 v86, v86
	s_nop 0
	v_add_f32_e32 v86, 1.0, v86
	v_rcp_f32_e32 v86, v86
	s_nop 0
	v_mul_f32_e32 v75, v75, v86
	v_mul_f32_e32 v86, 0x3d372713, v80
	v_mul_f32_e32 v86, v80, v86
	v_fma_f32 v86, v80, v86, v80
	v_mul_f32_e32 v86, 0x3f4c422a, v86
	v_mul_f32_e32 v86, 0xc038aa3b, v86
	v_exp_f32_e32 v86, v86
	s_nop 0
	v_add_f32_e32 v86, 1.0, v86
	v_rcp_f32_e32 v86, v86
	s_nop 0
	v_mul_f32_e32 v80, v80, v86
	v_mul_f32_e32 v86, 0x3d372713, v76
	v_mul_f32_e32 v86, v76, v86
	v_fma_f32 v86, v76, v86, v76
	v_mul_f32_e32 v86, 0x3f4c422a, v86
	v_mul_f32_e32 v86, 0xc038aa3b, v86
	v_exp_f32_e32 v86, v86
	s_nop 0
	v_add_f32_e32 v86, 1.0, v86
	v_rcp_f32_e32 v86, v86
	s_nop 0
	v_mul_f32_e32 v76, v76, v86
	v_mul_f32_e32 v86, 0x3d372713, v81
	v_mul_f32_e32 v86, v81, v86
	v_fma_f32 v86, v81, v86, v81
	v_mul_f32_e32 v86, 0x3f4c422a, v86
	v_mul_f32_e32 v86, 0xc038aa3b, v86
	v_exp_f32_e32 v86, v86
	s_nop 0
	v_add_f32_e32 v86, 1.0, v86
	v_rcp_f32_e32 v86, v86
	s_nop 0
	v_mul_f32_e32 v81, v81, v86
	v_mul_f32_e32 v86, 0x3d372713, v77
	v_mul_f32_e32 v86, v77, v86
	v_fma_f32 v86, v77, v86, v77
	v_mul_f32_e32 v86, 0x3f4c422a, v86
	v_mul_f32_e32 v86, 0xc038aa3b, v86
	v_exp_f32_e32 v86, v86
	s_nop 0
	v_add_f32_e32 v86, 1.0, v86
	v_rcp_f32_e32 v86, v86
	s_nop 0
	v_mul_f32_e32 v77, v77, v86
	v_cvt_pk_bf16_f32 v86, v78, v79
	v_cvt_pk_bf16_f32 v87, v80, v81
	v_cvt_pk_bf16_f32 v88, v74, v75
	v_cvt_pk_bf16_f32 v89, v76, v77
	s_waitcnt lgkmcnt(0)
	global_store_dwordx4 v224, v[230:233], s[98:99] offset:256
	s_nop 0
	v_readfirstlane_b32 s98, v84
	v_readfirstlane_b32 s99, v85
	ds_write_b128 v222, v[86:89]
	ds_read_b128 v[230:233], v223
	s_nop 1
	v_mul_f32_e32 v86, 0x3d372713, v70
	v_mul_f32_e32 v86, v70, v86
	v_fma_f32 v86, v70, v86, v70
	v_mul_f32_e32 v86, 0x3f4c422a, v86
	v_mul_f32_e32 v86, 0xc038aa3b, v86
	v_exp_f32_e32 v86, v86
	s_nop 0
	v_add_f32_e32 v86, 1.0, v86
	v_rcp_f32_e32 v86, v86
	s_nop 0
	v_mul_f32_e32 v70, v70, v86
	v_mul_f32_e32 v86, 0x3d372713, v66
	v_mul_f32_e32 v86, v66, v86
	v_fma_f32 v86, v66, v86, v66
	v_mul_f32_e32 v86, 0x3f4c422a, v86
	v_mul_f32_e32 v86, 0xc038aa3b, v86
	v_exp_f32_e32 v86, v86
	s_nop 0
	v_add_f32_e32 v86, 1.0, v86
	v_rcp_f32_e32 v86, v86
	s_nop 0
	v_mul_f32_e32 v66, v66, v86
	v_mul_f32_e32 v86, 0x3d372713, v71
	v_mul_f32_e32 v86, v71, v86
	v_fma_f32 v86, v71, v86, v71
	v_mul_f32_e32 v86, 0x3f4c422a, v86
	v_mul_f32_e32 v86, 0xc038aa3b, v86
	v_exp_f32_e32 v86, v86
	s_nop 0
	v_add_f32_e32 v86, 1.0, v86
	v_rcp_f32_e32 v86, v86
	s_nop 0
	v_mul_f32_e32 v71, v71, v86
	v_mul_f32_e32 v86, 0x3d372713, v67
	v_mul_f32_e32 v86, v67, v86
	v_fma_f32 v86, v67, v86, v67
	v_mul_f32_e32 v86, 0x3f4c422a, v86
	v_mul_f32_e32 v86, 0xc038aa3b, v86
	v_exp_f32_e32 v86, v86
	s_nop 0
	v_add_f32_e32 v86, 1.0, v86
	v_rcp_f32_e32 v86, v86
	s_nop 0
	v_mul_f32_e32 v67, v67, v86
	v_mul_f32_e32 v86, 0x3d372713, v72
	v_mul_f32_e32 v86, v72, v86
	v_fma_f32 v86, v72, v86, v72
	v_mul_f32_e32 v86, 0x3f4c422a, v86
	v_mul_f32_e32 v86, 0xc038aa3b, v86
	v_exp_f32_e32 v86, v86
	s_nop 0
	v_add_f32_e32 v86, 1.0, v86
	v_rcp_f32_e32 v86, v86
	s_nop 0
	v_mul_f32_e32 v72, v72, v86
	v_mul_f32_e32 v86, 0x3d372713, v68
	v_mul_f32_e32 v86, v68, v86
	v_fma_f32 v86, v68, v86, v68
	v_mul_f32_e32 v86, 0x3f4c422a, v86
	v_mul_f32_e32 v86, 0xc038aa3b, v86
	v_exp_f32_e32 v86, v86
	s_nop 0
	v_add_f32_e32 v86, 1.0, v86
	v_rcp_f32_e32 v86, v86
	s_nop 0
	v_mul_f32_e32 v68, v68, v86
	v_mul_f32_e32 v86, 0x3d372713, v73
	v_mul_f32_e32 v86, v73, v86
	v_fma_f32 v86, v73, v86, v73
	v_mul_f32_e32 v86, 0x3f4c422a, v86
	v_mul_f32_e32 v86, 0xc038aa3b, v86
	v_exp_f32_e32 v86, v86
	s_nop 0
	v_add_f32_e32 v86, 1.0, v86
	v_rcp_f32_e32 v86, v86
	s_nop 0
	v_mul_f32_e32 v73, v73, v86
	v_mul_f32_e32 v86, 0x3d372713, v69
	v_mul_f32_e32 v86, v69, v86
	v_fma_f32 v86, v69, v86, v69
	v_mul_f32_e32 v86, 0x3f4c422a, v86
	v_mul_f32_e32 v86, 0xc038aa3b, v86
	v_exp_f32_e32 v86, v86
	s_nop 0
	v_add_f32_e32 v86, 1.0, v86
	v_rcp_f32_e32 v86, v86
	s_nop 0
	v_mul_f32_e32 v69, v69, v86
	v_cvt_pk_bf16_f32 v86, v70, v71
	v_cvt_pk_bf16_f32 v87, v72, v73
	v_cvt_pk_bf16_f32 v88, v66, v67
	v_cvt_pk_bf16_f32 v89, v68, v69
	s_waitcnt lgkmcnt(0)
	global_store_dwordx4 v224, v[230:233], s[98:99]
	s_nop 0
	v_readfirstlane_b32 s98, v84
	v_readfirstlane_b32 s99, v85
	ds_write_b128 v222, v[86:89]
	ds_read_b128 v[230:233], v223
	s_cbranch_vccnz .LBB0_230
; __device__ __forceinline__ unsigned cvt_pk_bf16(float lo, float hi) { unsigned r; asm volatile("v_cvt_pk_bf16_f32 %0, %1, %2" : "=v"(r) : "v"(lo), "v"(hi)); return r; }
; __device__ __forceinline__ float quad_sum(float s) { s += __shfl_xor(s, 16); s += __shfl_xor(s, 32); return s; }
;     __device__ __forceinline__ void operator()(const f32x4 (&acc)[2][2][4][2], const Unit& u, int wr, int wc, int fr, int fq) const {
;     ...
;                         s1 += (v0[0] + v0[1]) + (v0[2] + v0[3]) + (v1[0] + v1[1]) + (v1[2] + v1[3]);
;                         s2 += (v0[0] * v0[0] + v0[1] * v0[1]) + (v0[2] * v0[2] + v0[3] * v0[3]) + (v1[0] * v1[0] + v1[1] * v1[1]) + (v1[2] * v1[2] + v1[3] * v1[3]);
;                         u32x4 w; w.x = cvt_pk_bf16(v0[0], v0[1]); w.y = cvt_pk_bf16(v0[2], v0[3]); w.z = cvt_pk_bf16(v1[0], v1[1]); w.w = cvt_pk_bf16(v1[2], v1[3]);
;                         *(u32x4*)(rowp + bj * HALF) = w; }
;                     if (stats) { s1 = quad_sum(s1); s2 = quad_sum(s2); if (fq == 0) { atomicAdd(st1 + row, s1); atomicAdd(st2 + row, s2); } } }
	s_nop 0
	v_mul_f32_e32 v86, v79, v79
	v_mul_f32_e32 v87, v81, v81
	v_mul_f32_e32 v85, v75, v75
	v_fmac_f32_e32 v86, v78, v78
	v_fmac_f32_e32 v87, v80, v80
	v_mul_f32_e32 v84, v77, v77
	v_fmac_f32_e32 v85, v74, v74
	v_add_f32_e32 v86, v86, v87
	v_fmac_f32_e32 v84, v76, v76
	v_add_f32_e32 v85, v86, v85
	v_add_f32_e32 v84, v84, v85
	v_mul_f32_e32 v85, v69, v69
	v_mul_f32_e32 v86, v67, v67
	v_fmac_f32_e32 v85, v68, v68
	v_fmac_f32_e32 v86, v66, v66
	v_add_f32_e32 v68, v68, v69
	v_add_f32_e32 v66, v66, v67
	v_add_f32_e32 v67, v70, v71
	v_add_f32_e32 v69, v72, v73
	v_add_f32_e32 v67, v67, v69
	v_add_f32_e32 v76, v76, v77
	v_add_f32_e32 v74, v74, v75
	v_add_f32_e32 v75, v78, v79
	v_add_f32_e32 v77, v80, v81
	v_add_f32_e32 v66, v67, v66
	v_add_f32_e32 v75, v75, v77
	v_add_f32_e32 v66, v68, v66
	v_and_b32_e32 v68, 64, v183
	v_add_f32_e32 v74, v75, v74
	v_xor_b32_e32 v67, 16, v183
	v_add_u32_e32 v68, 64, v68
	v_mul_f32_e32 v87, v71, v71
	v_mul_f32_e32 v88, v73, v73
	v_add_f32_e32 v74, v76, v74
	v_cmp_lt_i32_e32 vcc, v67, v68
	v_fmac_f32_e32 v87, v70, v70
	v_fmac_f32_e32 v88, v72, v72
	v_add_f32_e32 v74, 0, v74
	v_cndmask_b32_e32 v67, v183, v67, vcc
	v_add_f32_e32 v66, v74, v66
	v_lshlrev_b32_e32 v67, 2, v67
	v_add_f32_e32 v70, v87, v88
	ds_bpermute_b32 v69, v67, v66
	v_add_f32_e32 v70, v70, v86
	v_add_f32_e32 v70, v85, v70
	v_add_f32_e32 v70, v84, v70
	ds_bpermute_b32 v71, v67, v70
	s_waitcnt lgkmcnt(0)
	v_add_f32_e32 v66, v66, v69
	v_xor_b32_e32 v69, 32, v183
	v_cmp_lt_i32_e32 vcc, v69, v68
	v_add_f32_e32 v68, v70, v71
	s_nop 0
	v_cndmask_b32_e32 v67, v183, v69, vcc
	v_lshlrev_b32_e32 v69, 2, v67
	ds_bpermute_b32 v67, v69, v66
	ds_bpermute_b32 v69, v69, v68
	s_and_saveexec_b64 s[8:9], s[2:3]
	s_cbranch_execz .LBB0_229
	v_lshlrev_b64 v[70:71], 2, v[82:83]
	v_lshl_add_u64 v[72:73], s[78:79], 0, v[70:71]
	v_lshl_add_u64 v[70:71], s[76:77], 0, v[70:71]
	s_waitcnt lgkmcnt(0)
	v_add_f32_e32 v66, v66, v67
	v_add_f32_e32 v68, v68, v69
	global_atomic_add_f32 v[70:71], v66, off
	global_atomic_add_f32 v[72:73], v68, off

; __device__ __forceinline__ unsigned cvt_pk_bf16(float lo, float hi) { unsigned r; asm volatile("v_cvt_pk_bf16_f32 %0, %1, %2" : "=v"(r) : "v"(lo), "v"(hi)); return r; }
; __device__ __forceinline__ float gelu_t(float x) { const float u = 0.7978845608028654f * (x + 0.044715f * x * x * x); return x * fast_rcp(1.0f + fast_exp2(-2.8853900817779268f * u)); }
;     __device__ __forceinline__ void operator()(const f32x4 (&acc)[2][2][4][2], const Unit& u, int wr, int wc, int fr, int fq) const {
;     ...
;                 for (int m = 0; m < 4; ++m) { const int row = row0 + ai * HALF + m * 16; bf16_t* rowp = dst + (size_t)row * 512 + col0; float s1 = 0.f, s2 = 0.f;
; #pragma unroll
;                     for (int bj = 0; bj < 2; ++bj) { f32x4 v0 = acc[ai][bj][m][0], v1 = acc[ai][bj][m][1];
; #pragma unroll
;                         for (int j = 0; j < 4; ++j) { v0[j] = gelu_t(v0[j]); v1[j] = gelu_t(v1[j]); }
;                         s1 += (v0[0] + v0[1]) + (v0[2] + v0[3]) + (v1[0] + v1[1]) + (v1[2] + v1[3]);
;                         s2 += (v0[0] * v0[0] + v0[1] * v0[1]) + (v0[2] * v0[2] + v0[3] * v0[3]) + (v1[0] * v1[0] + v1[1] * v1[1]) + (v1[2] * v1[2] + v1[3] * v1[3]);
;                         u32x4 w; w.x = cvt_pk_bf16(v0[0], v0[1]); w.y = cvt_pk_bf16(v0[2], v0[3]); w.z = cvt_pk_bf16(v1[0], v1[1]); w.w = cvt_pk_bf16(v1[2], v1[3]);
;                         *(u32x4*)(rowp + bj * HALF) = w; }
.LBB0_230:
	v_mul_f32_e32 v70, 0x3d372713, v62
	v_mul_f32_e32 v70, v62, v70
	v_fma_f32 v70, v62, v70, v62
	v_mul_f32_e32 v70, 0x3f4c422a, v70
	v_mul_f32_e32 v70, 0xc038aa3b, v70
	v_exp_f32_e32 v70, v70
	v_add_u32_e32 v66, 0x80, v166
	s_waitcnt lgkmcnt(0)
	v_ashrrev_i32_e32 v67, 31, v66
	v_lshlrev_b64 v[68:69], 10, v[66:67]
	v_add_f32_e32 v70, 1.0, v70
	v_rcp_f32_e32 v70, v70
	v_lshl_add_u64 v[68:69], v[130:131], 0, v[68:69]
	s_and_b64 vcc, exec, s[6:7]
	v_mul_f32_e32 v62, v62, v70
	v_mul_f32_e32 v70, 0x3d372713, v58
	v_mul_f32_e32 v70, v58, v70
	v_fma_f32 v70, v58, v70, v58
	v_mul_f32_e32 v70, 0x3f4c422a, v70
	v_mul_f32_e32 v70, 0xc038aa3b, v70
	v_exp_f32_e32 v70, v70
	s_nop 0
	v_add_f32_e32 v70, 1.0, v70
	v_rcp_f32_e32 v70, v70
	s_nop 0
	v_mul_f32_e32 v58, v58, v70
	v_mul_f32_e32 v70, 0x3d372713, v63
	v_mul_f32_e32 v70, v63, v70
	v_fma_f32 v70, v63, v70, v63
	v_mul_f32_e32 v70, 0x3f4c422a, v70
	v_mul_f32_e32 v70, 0xc038aa3b, v70
	v_exp_f32_e32 v70, v70
	s_nop 0
	v_add_f32_e32 v70, 1.0, v70
	v_rcp_f32_e32 v70, v70
	s_nop 0
	v_mul_f32_e32 v63, v63, v70
	v_mul_f32_e32 v70, 0x3d372713, v59
	v_mul_f32_e32 v70, v59, v70
	v_fma_f32 v70, v59, v70, v59
	v_mul_f32_e32 v70, 0x3f4c422a, v70
	v_mul_f32_e32 v70, 0xc038aa3b, v70
	v_exp_f32_e32 v70, v70
	s_nop 0
	v_add_f32_e32 v70, 1.0, v70
	v_rcp_f32_e32 v70, v70
	s_nop 0
	v_mul_f32_e32 v59, v59, v70
	v_mul_f32_e32 v70, 0x3d372713, v64
	v_mul_f32_e32 v70, v64, v70
	v_fma_f32 v70, v64, v70, v64
	v_mul_f32_e32 v70, 0x3f4c422a, v70
	v_mul_f32_e32 v70, 0xc038aa3b, v70
	v_exp_f32_e32 v70, v70
	s_nop 0
	v_add_f32_e32 v70, 1.0, v70
	v_rcp_f32_e32 v70, v70
	s_nop 0
	v_mul_f32_e32 v64, v64, v70
	v_mul_f32_e32 v70, 0x3d372713, v60
	v_mul_f32_e32 v70, v60, v70
	v_fma_f32 v70, v60, v70, v60
	v_mul_f32_e32 v70, 0x3f4c422a, v70
	v_mul_f32_e32 v70, 0xc038aa3b, v70
	v_exp_f32_e32 v70, v70
	s_nop 0
	v_add_f32_e32 v70, 1.0, v70
	v_rcp_f32_e32 v70, v70
	s_nop 0
	v_mul_f32_e32 v60, v60, v70
	v_mul_f32_e32 v70, 0x3d372713, v65
	v_mul_f32_e32 v70, v65, v70
	v_fma_f32 v70, v65, v70, v65
	v_mul_f32_e32 v70, 0x3f4c422a, v70
	v_mul_f32_e32 v70, 0xc038aa3b, v70
	v_exp_f32_e32 v70, v70
	s_nop 0
	v_add_f32_e32 v70, 1.0, v70
	v_rcp_f32_e32 v70, v70
	s_nop 0
	v_mul_f32_e32 v65, v65, v70
	v_mul_f32_e32 v70, 0x3d372713, v61
	v_mul_f32_e32 v70, v61, v70
	v_fma_f32 v70, v61, v70, v61
	v_mul_f32_e32 v70, 0x3f4c422a, v70
	v_mul_f32_e32 v70, 0xc038aa3b, v70
	v_exp_f32_e32 v70, v70
	s_nop 0
	v_add_f32_e32 v70, 1.0, v70
	v_rcp_f32_e32 v70, v70
	s_nop 0
	v_mul_f32_e32 v61, v61, v70
	v_cvt_pk_bf16_f32 v70, v62, v63
	v_cvt_pk_bf16_f32 v71, v64, v65
	v_cvt_pk_bf16_f32 v72, v58, v59
	v_cvt_pk_bf16_f32 v73, v60, v61
	s_waitcnt lgkmcnt(0)
	global_store_dwordx4 v224, v[230:233], s[98:99] offset:256
	s_nop 0
	v_readfirstlane_b32 s98, v68
	v_readfirstlane_b32 s99, v69
	ds_write_b128 v222, v[70:73]
	ds_read_b128 v[230:233], v223
	s_nop 1
	v_mul_f32_e32 v70, 0x3d372713, v54
	v_mul_f32_e32 v70, v54, v70
	v_fma_f32 v70, v54, v70, v54
	v_mul_f32_e32 v70, 0x3f4c422a, v70
	v_mul_f32_e32 v70, 0xc038aa3b, v70
	v_exp_f32_e32 v70, v70
	s_nop 0
	v_add_f32_e32 v70, 1.0, v70
	v_rcp_f32_e32 v70, v70
	s_nop 0
	v_mul_f32_e32 v54, v54, v70
	v_mul_f32_e32 v70, 0x3d372713, v50
	v_mul_f32_e32 v70, v50, v70
	v_fma_f32 v70, v50, v70, v50
	v_mul_f32_e32 v70, 0x3f4c422a, v70
	v_mul_f32_e32 v70, 0xc038aa3b, v70
	v_exp_f32_e32 v70, v70
	s_nop 0
	v_add_f32_e32 v70, 1.0, v70
	v_rcp_f32_e32 v70, v70
	s_nop 0
	v_mul_f32_e32 v50, v50, v70
	v_mul_f32_e32 v70, 0x3d372713, v55
	v_mul_f32_e32 v70, v55, v70
	v_fma_f32 v70, v55, v70, v55
	v_mul_f32_e32 v70, 0x3f4c422a, v70
	v_mul_f32_e32 v70, 0xc038aa3b, v70
	v_exp_f32_e32 v70, v70
	s_nop 0
	v_add_f32_e32 v70, 1.0, v70
	v_rcp_f32_e32 v70, v70
	s_nop 0
	v_mul_f32_e32 v55, v55, v70
	v_mul_f32_e32 v70, 0x3d372713, v51
	v_mul_f32_e32 v70, v51, v70
	v_fma_f32 v70, v51, v70, v51
	v_mul_f32_e32 v70, 0x3f4c422a, v70
	v_mul_f32_e32 v70, 0xc038aa3b, v70
	v_exp_f32_e32 v70, v70
	s_nop 0
	v_add_f32_e32 v70, 1.0, v70
	v_rcp_f32_e32 v70, v70
	s_nop 0
	v_mul_f32_e32 v51, v51, v70
	v_mul_f32_e32 v70, 0x3d372713, v56
	v_mul_f32_e32 v70, v56, v70
	v_fma_f32 v70, v56, v70, v56
	v_mul_f32_e32 v70, 0x3f4c422a, v70
	v_mul_f32_e32 v70, 0xc038aa3b, v70
	v_exp_f32_e32 v70, v70
	s_nop 0
	v_add_f32_e32 v70, 1.0, v70
	v_rcp_f32_e32 v70, v70
	s_nop 0
	v_mul_f32_e32 v56, v56, v70
	v_mul_f32_e32 v70, 0x3d372713, v52
	v_mul_f32_e32 v70, v52, v70
	v_fma_f32 v70, v52, v70, v52
	v_mul_f32_e32 v70, 0x3f4c422a, v70
	v_mul_f32_e32 v70, 0xc038aa3b, v70
	v_exp_f32_e32 v70, v70
	s_nop 0
	v_add_f32_e32 v70, 1.0, v70
	v_rcp_f32_e32 v70, v70
	s_nop 0
	v_mul_f32_e32 v52, v52, v70
	v_mul_f32_e32 v70, 0x3d372713, v57
	v_mul_f32_e32 v70, v57, v70
	v_fma_f32 v70, v57, v70, v57
	v_mul_f32_e32 v70, 0x3f4c422a, v70
	v_mul_f32_e32 v70, 0xc038aa3b, v70
	v_exp_f32_e32 v70, v70
	s_nop 0
	v_add_f32_e32 v70, 1.0, v70
	v_rcp_f32_e32 v70, v70
	s_nop 0
	v_mul_f32_e32 v57, v57, v70
	v_mul_f32_e32 v70, 0x3d372713, v53
	v_mul_f32_e32 v70, v53, v70
	v_fma_f32 v70, v53, v70, v53
	v_mul_f32_e32 v70, 0x3f4c422a, v70
	v_mul_f32_e32 v70, 0xc038aa3b, v70
	v_exp_f32_e32 v70, v70
	s_nop 0
	v_add_f32_e32 v70, 1.0, v70
	v_rcp_f32_e32 v70, v70
	s_nop 0
	v_mul_f32_e32 v53, v53, v70
	v_cvt_pk_bf16_f32 v70, v54, v55
	v_cvt_pk_bf16_f32 v71, v56, v57
	v_cvt_pk_bf16_f32 v72, v50, v51
	v_cvt_pk_bf16_f32 v73, v52, v53
	s_waitcnt lgkmcnt(0)
	global_store_dwordx4 v224, v[230:233], s[98:99]
	s_nop 0
	v_readfirstlane_b32 s98, v68
	v_readfirstlane_b32 s99, v69
	ds_write_b128 v222, v[70:73]
	ds_read_b128 v[230:233], v223
	s_cbranch_vccnz .LBB0_234
; __device__ __forceinline__ unsigned cvt_pk_bf16(float lo, float hi) { unsigned r; asm volatile("v_cvt_pk_bf16_f32 %0, %1, %2" : "=v"(r) : "v"(lo), "v"(hi)); return r; }
; __device__ __forceinline__ float quad_sum(float s) { s += __shfl_xor(s, 16); s += __shfl_xor(s, 32); return s; }
;     __device__ __forceinline__ void operator()(const f32x4 (&acc)[2][2][4][2], const Unit& u, int wr, int wc, int fr, int fq) const {
;     ...
;                         s1 += (v0[0] + v0[1]) + (v0[2] + v0[3]) + (v1[0] + v1[1]) + (v1[2] + v1[3]);
;                         s2 += (v0[0] * v0[0] + v0[1] * v0[1]) + (v0[2] * v0[2] + v0[3] * v0[3]) + (v1[0] * v1[0] + v1[1] * v1[1]) + (v1[2] * v1[2] + v1[3] * v1[3]);
;                         u32x4 w; w.x = cvt_pk_bf16(v0[0], v0[1]); w.y = cvt_pk_bf16(v0[2], v0[3]); w.z = cvt_pk_bf16(v1[0], v1[1]); w.w = cvt_pk_bf16(v1[2], v1[3]);
;                         *(u32x4*)(rowp + bj * HALF) = w; }
;                     if (stats) { s1 = quad_sum(s1); s2 = quad_sum(s2); if (fq == 0) { atomicAdd(st1 + row, s1); atomicAdd(st2 + row, s2); } } }
	s_nop 0
	v_mul_f32_e32 v70, v63, v63
	v_mul_f32_e32 v71, v65, v65
	v_mul_f32_e32 v69, v59, v59
	v_fmac_f32_e32 v70, v62, v62
	v_fmac_f32_e32 v71, v64, v64
	v_mul_f32_e32 v68, v61, v61
	v_fmac_f32_e32 v69, v58, v58
	v_add_f32_e32 v70, v70, v71
	v_fmac_f32_e32 v68, v60, v60
	v_add_f32_e32 v69, v70, v69
	v_add_f32_e32 v68, v68, v69
	v_mul_f32_e32 v69, v53, v53
	v_mul_f32_e32 v70, v51, v51
	v_fmac_f32_e32 v69, v52, v52
	v_fmac_f32_e32 v70, v50, v50
	v_add_f32_e32 v52, v52, v53
	v_add_f32_e32 v50, v50, v51
	v_add_f32_e32 v51, v54, v55
	v_add_f32_e32 v53, v56, v57
	v_add_f32_e32 v51, v51, v53
	v_add_f32_e32 v60, v60, v61
	v_add_f32_e32 v58, v58, v59
	v_add_f32_e32 v59, v62, v63
	v_add_f32_e32 v61, v64, v65
	v_add_f32_e32 v50, v51, v50
	v_add_f32_e32 v59, v59, v61
	v_add_f32_e32 v50, v52, v50
	v_and_b32_e32 v52, 64, v183
	v_add_f32_e32 v58, v59, v58
	v_xor_b32_e32 v51, 16, v183
	v_add_u32_e32 v52, 64, v52
	v_mul_f32_e32 v71, v55, v55
	v_mul_f32_e32 v72, v57, v57
	v_add_f32_e32 v58, v60, v58
	v_cmp_lt_i32_e32 vcc, v51, v52
	v_fmac_f32_e32 v71, v54, v54
	v_fmac_f32_e32 v72, v56, v56
	v_add_f32_e32 v58, 0, v58
	v_cndmask_b32_e32 v51, v183, v51, vcc
	v_add_f32_e32 v50, v58, v50
	v_lshlrev_b32_e32 v51, 2, v51
	v_add_f32_e32 v54, v71, v72
	ds_bpermute_b32 v53, v51, v50
	v_add_f32_e32 v54, v54, v70
	v_add_f32_e32 v54, v69, v54
	v_add_f32_e32 v54, v68, v54
	ds_bpermute_b32 v55, v51, v54
	s_waitcnt lgkmcnt(0)
	v_add_f32_e32 v50, v50, v53
	v_xor_b32_e32 v53, 32, v183
	v_cmp_lt_i32_e32 vcc, v53, v52
	v_add_f32_e32 v52, v54, v55
	s_nop 0
	v_cndmask_b32_e32 v51, v183, v53, vcc
	v_lshlrev_b32_e32 v53, 2, v51
	ds_bpermute_b32 v51, v53, v50
	ds_bpermute_b32 v53, v53, v52
	s_and_saveexec_b64 s[8:9], s[2:3]
	s_cbranch_execz .LBB0_233
	v_lshlrev_b64 v[54:55], 2, v[66:67]
	v_lshl_add_u64 v[56:57], s[78:79], 0, v[54:55]
	v_lshl_add_u64 v[54:55], s[76:77], 0, v[54:55]
	s_waitcnt lgkmcnt(0)
	v_add_f32_e32 v50, v50, v51
	v_add_f32_e32 v52, v52, v53
	global_atomic_add_f32 v[54:55], v50, off
	global_atomic_add_f32 v[56:57], v52, off

; __device__ __forceinline__ unsigned cvt_pk_bf16(float lo, float hi) { unsigned r; asm volatile("v_cvt_pk_bf16_f32 %0, %1, %2" : "=v"(r) : "v"(lo), "v"(hi)); return r; }
; __device__ __forceinline__ float gelu_t(float x) { const float u = 0.7978845608028654f * (x + 0.044715f * x * x * x); return x * fast_rcp(1.0f + fast_exp2(-2.8853900817779268f * u)); }
;     __device__ __forceinline__ void operator()(const f32x4 (&acc)[2][2][4][2], const Unit& u, int wr, int wc, int fr, int fq) const {
;     ...
;                 for (int m = 0; m < 4; ++m) { const int row = row0 + ai * HALF + m * 16; bf16_t* rowp = dst + (size_t)row * 512 + col0; float s1 = 0.f, s2 = 0.f;
; #pragma unroll
;                     for (int bj = 0; bj < 2; ++bj) { f32x4 v0 = acc[ai][bj][m][0], v1 = acc[ai][bj][m][1];
; #pragma unroll
;                         for (int j = 0; j < 4; ++j) { v0[j] = gelu_t(v0[j]); v1[j] = gelu_t(v1[j]); }
;                         s1 += (v0[0] + v0[1]) + (v0[2] + v0[3]) + (v1[0] + v1[1]) + (v1[2] + v1[3]);
;                         s2 += (v0[0] * v0[0] + v0[1] * v0[1]) + (v0[2] * v0[2] + v0[3] * v0[3]) + (v1[0] * v1[0] + v1[1] * v1[1]) + (v1[2] * v1[2] + v1[3] * v1[3]);
;                         u32x4 w; w.x = cvt_pk_bf16(v0[0], v0[1]); w.y = cvt_pk_bf16(v0[2], v0[3]); w.z = cvt_pk_bf16(v1[0], v1[1]); w.w = cvt_pk_bf16(v1[2], v1[3]);
;                         *(u32x4*)(rowp + bj * HALF) = w; }
.LBB0_234:
	v_mul_f32_e32 v54, 0x3d372713, v46
	v_mul_f32_e32 v54, v46, v54
	v_fma_f32 v54, v46, v54, v46
	v_mul_f32_e32 v54, 0x3f4c422a, v54
	v_mul_f32_e32 v54, 0xc038aa3b, v54
	v_exp_f32_e32 v54, v54
	v_add_u32_e32 v50, 0x90, v166
	s_waitcnt lgkmcnt(0)
	v_ashrrev_i32_e32 v51, 31, v50
	v_lshlrev_b64 v[52:53], 10, v[50:51]
	v_add_f32_e32 v54, 1.0, v54
	v_rcp_f32_e32 v54, v54
	v_lshl_add_u64 v[52:53], v[130:131], 0, v[52:53]
	s_and_b64 vcc, exec, s[6:7]
	v_mul_f32_e32 v46, v46, v54
	v_mul_f32_e32 v54, 0x3d372713, v42
	v_mul_f32_e32 v54, v42, v54
	v_fma_f32 v54, v42, v54, v42
	v_mul_f32_e32 v54, 0x3f4c422a, v54
	v_mul_f32_e32 v54, 0xc038aa3b, v54
	v_exp_f32_e32 v54, v54
	s_nop 0
	v_add_f32_e32 v54, 1.0, v54
	v_rcp_f32_e32 v54, v54
	s_nop 0
	v_mul_f32_e32 v42, v42, v54
	v_mul_f32_e32 v54, 0x3d372713, v47
	v_mul_f32_e32 v54, v47, v54
	v_fma_f32 v54, v47, v54, v47
	v_mul_f32_e32 v54, 0x3f4c422a, v54
	v_mul_f32_e32 v54, 0xc038aa3b, v54
	v_exp_f32_e32 v54, v54
	s_nop 0
	v_add_f32_e32 v54, 1.0, v54
	v_rcp_f32_e32 v54, v54
	s_nop 0
	v_mul_f32_e32 v47, v47, v54
	v_mul_f32_e32 v54, 0x3d372713, v43
	v_mul_f32_e32 v54, v43, v54
	v_fma_f32 v54, v43, v54, v43
	v_mul_f32_e32 v54, 0x3f4c422a, v54
	v_mul_f32_e32 v54, 0xc038aa3b, v54
	v_exp_f32_e32 v54, v54
	s_nop 0
	v_add_f32_e32 v54, 1.0, v54
	v_rcp_f32_e32 v54, v54
	s_nop 0
	v_mul_f32_e32 v43, v43, v54
	v_mul_f32_e32 v54, 0x3d372713, v48
	v_mul_f32_e32 v54, v48, v54
	v_fma_f32 v54, v48, v54, v48
	v_mul_f32_e32 v54, 0x3f4c422a, v54
	v_mul_f32_e32 v54, 0xc038aa3b, v54
	v_exp_f32_e32 v54, v54
	s_nop 0
	v_add_f32_e32 v54, 1.0, v54
	v_rcp_f32_e32 v54, v54
	s_nop 0
	v_mul_f32_e32 v48, v48, v54
	v_mul_f32_e32 v54, 0x3d372713, v44
	v_mul_f32_e32 v54, v44, v54
	v_fma_f32 v54, v44, v54, v44
	v_mul_f32_e32 v54, 0x3f4c422a, v54
	v_mul_f32_e32 v54, 0xc038aa3b, v54
	v_exp_f32_e32 v54, v54
	s_nop 0
	v_add_f32_e32 v54, 1.0, v54
	v_rcp_f32_e32 v54, v54
	s_nop 0
	v_mul_f32_e32 v44, v44, v54
	v_mul_f32_e32 v54, 0x3d372713, v49
	v_mul_f32_e32 v54, v49, v54
	v_fma_f32 v54, v49, v54, v49
	v_mul_f32_e32 v54, 0x3f4c422a, v54
	v_mul_f32_e32 v54, 0xc038aa3b, v54
	v_exp_f32_e32 v54, v54
	s_nop 0
	v_add_f32_e32 v54, 1.0, v54
	v_rcp_f32_e32 v54, v54
	s_nop 0
	v_mul_f32_e32 v49, v49, v54
	v_mul_f32_e32 v54, 0x3d372713, v45
	v_mul_f32_e32 v54, v45, v54
	v_fma_f32 v54, v45, v54, v45
	v_mul_f32_e32 v54, 0x3f4c422a, v54
	v_mul_f32_e32 v54, 0xc038aa3b, v54
	v_exp_f32_e32 v54, v54
	s_nop 0
	v_add_f32_e32 v54, 1.0, v54
	v_rcp_f32_e32 v54, v54
	s_nop 0
	v_mul_f32_e32 v45, v45, v54
	v_cvt_pk_bf16_f32 v54, v46, v47
	v_cvt_pk_bf16_f32 v55, v48, v49
	v_cvt_pk_bf16_f32 v56, v42, v43
	v_cvt_pk_bf16_f32 v57, v44, v45
	s_waitcnt lgkmcnt(0)
	global_store_dwordx4 v224, v[230:233], s[98:99] offset:256
	s_nop 0
	v_readfirstlane_b32 s98, v52
	v_readfirstlane_b32 s99, v53
	ds_write_b128 v222, v[54:57]
	ds_read_b128 v[230:233], v223
	s_nop 1
	v_mul_f32_e32 v54, 0x3d372713, v38
	v_mul_f32_e32 v54, v38, v54
	v_fma_f32 v54, v38, v54, v38
	v_mul_f32_e32 v54, 0x3f4c422a, v54
	v_mul_f32_e32 v54, 0xc038aa3b, v54
	v_exp_f32_e32 v54, v54
	s_nop 0
	v_add_f32_e32 v54, 1.0, v54
	v_rcp_f32_e32 v54, v54
	s_nop 0
	v_mul_f32_e32 v38, v38, v54
	v_mul_f32_e32 v54, 0x3d372713, v34
	v_mul_f32_e32 v54, v34, v54
	v_fma_f32 v54, v34, v54, v34
	v_mul_f32_e32 v54, 0x3f4c422a, v54
	v_mul_f32_e32 v54, 0xc038aa3b, v54
	v_exp_f32_e32 v54, v54
	s_nop 0
	v_add_f32_e32 v54, 1.0, v54
	v_rcp_f32_e32 v54, v54
	s_nop 0
	v_mul_f32_e32 v34, v34, v54
	v_mul_f32_e32 v54, 0x3d372713, v39
	v_mul_f32_e32 v54, v39, v54
	v_fma_f32 v54, v39, v54, v39
	v_mul_f32_e32 v54, 0x3f4c422a, v54
	v_mul_f32_e32 v54, 0xc038aa3b, v54
	v_exp_f32_e32 v54, v54
	s_nop 0
	v_add_f32_e32 v54, 1.0, v54
	v_rcp_f32_e32 v54, v54
	s_nop 0
	v_mul_f32_e32 v39, v39, v54
	v_mul_f32_e32 v54, 0x3d372713, v35
	v_mul_f32_e32 v54, v35, v54
	v_fma_f32 v54, v35, v54, v35
	v_mul_f32_e32 v54, 0x3f4c422a, v54
	v_mul_f32_e32 v54, 0xc038aa3b, v54
	v_exp_f32_e32 v54, v54
	s_nop 0
	v_add_f32_e32 v54, 1.0, v54
	v_rcp_f32_e32 v54, v54
	s_nop 0
	v_mul_f32_e32 v35, v35, v54
	v_mul_f32_e32 v54, 0x3d372713, v40
	v_mul_f32_e32 v54, v40, v54
	v_fma_f32 v54, v40, v54, v40
	v_mul_f32_e32 v54, 0x3f4c422a, v54
	v_mul_f32_e32 v54, 0xc038aa3b, v54
	v_exp_f32_e32 v54, v54
	s_nop 0
	v_add_f32_e32 v54, 1.0, v54
	v_rcp_f32_e32 v54, v54
	s_nop 0
	v_mul_f32_e32 v40, v40, v54
	v_mul_f32_e32 v54, 0x3d372713, v36
	v_mul_f32_e32 v54, v36, v54
	v_fma_f32 v54, v36, v54, v36
	v_mul_f32_e32 v54, 0x3f4c422a, v54
	v_mul_f32_e32 v54, 0xc038aa3b, v54
	v_exp_f32_e32 v54, v54
	s_nop 0
	v_add_f32_e32 v54, 1.0, v54
	v_rcp_f32_e32 v54, v54
	s_nop 0
	v_mul_f32_e32 v36, v36, v54
	v_mul_f32_e32 v54, 0x3d372713, v41
	v_mul_f32_e32 v54, v41, v54
	v_fma_f32 v54, v41, v54, v41
	v_mul_f32_e32 v54, 0x3f4c422a, v54
	v_mul_f32_e32 v54, 0xc038aa3b, v54
	v_exp_f32_e32 v54, v54
	s_nop 0
	v_add_f32_e32 v54, 1.0, v54
	v_rcp_f32_e32 v54, v54
	s_nop 0
	v_mul_f32_e32 v41, v41, v54
	v_mul_f32_e32 v54, 0x3d372713, v37
	v_mul_f32_e32 v54, v37, v54
	v_fma_f32 v54, v37, v54, v37
	v_mul_f32_e32 v54, 0x3f4c422a, v54
	v_mul_f32_e32 v54, 0xc038aa3b, v54
	v_exp_f32_e32 v54, v54
	s_nop 0
	v_add_f32_e32 v54, 1.0, v54
	v_rcp_f32_e32 v54, v54
	s_nop 0
	v_mul_f32_e32 v37, v37, v54
	v_cvt_pk_bf16_f32 v54, v38, v39
	v_cvt_pk_bf16_f32 v55, v40, v41
	v_cvt_pk_bf16_f32 v56, v34, v35
	v_cvt_pk_bf16_f32 v57, v36, v37
	s_waitcnt lgkmcnt(0)
	global_store_dwordx4 v224, v[230:233], s[98:99]
	s_nop 0
	v_readfirstlane_b32 s98, v52
	v_readfirstlane_b32 s99, v53
	ds_write_b128 v222, v[54:57]
	ds_read_b128 v[230:233], v223
	s_cbranch_vccnz .LBB0_238
; __device__ __forceinline__ unsigned cvt_pk_bf16(float lo, float hi) { unsigned r; asm volatile("v_cvt_pk_bf16_f32 %0, %1, %2" : "=v"(r) : "v"(lo), "v"(hi)); return r; }
; __device__ __forceinline__ float quad_sum(float s) { s += __shfl_xor(s, 16); s += __shfl_xor(s, 32); return s; }
;     __device__ __forceinline__ void operator()(const f32x4 (&acc)[2][2][4][2], const Unit& u, int wr, int wc, int fr, int fq) const {
;     ...
;                         s1 += (v0[0] + v0[1]) + (v0[2] + v0[3]) + (v1[0] + v1[1]) + (v1[2] + v1[3]);
;                         s2 += (v0[0] * v0[0] + v0[1] * v0[1]) + (v0[2] * v0[2] + v0[3] * v0[3]) + (v1[0] * v1[0] + v1[1] * v1[1]) + (v1[2] * v1[2] + v1[3] * v1[3]);
;                         u32x4 w; w.x = cvt_pk_bf16(v0[0], v0[1]); w.y = cvt_pk_bf16(v0[2], v0[3]); w.z = cvt_pk_bf16(v1[0], v1[1]); w.w = cvt_pk_bf16(v1[2], v1[3]);
;                         *(u32x4*)(rowp + bj * HALF) = w; }
;                     if (stats) { s1 = quad_sum(s1); s2 = quad_sum(s2); if (fq == 0) { atomicAdd(st1 + row, s1); atomicAdd(st2 + row, s2); } } }
	s_nop 0
	v_mul_f32_e32 v54, v47, v47
	v_mul_f32_e32 v55, v49, v49
	v_mul_f32_e32 v53, v43, v43
	v_fmac_f32_e32 v54, v46, v46
	v_fmac_f32_e32 v55, v48, v48
	v_mul_f32_e32 v52, v45, v45
	v_fmac_f32_e32 v53, v42, v42
	v_add_f32_e32 v54, v54, v55
	v_fmac_f32_e32 v52, v44, v44
	v_add_f32_e32 v53, v54, v53
	v_add_f32_e32 v52, v52, v53
	v_mul_f32_e32 v53, v37, v37
	v_mul_f32_e32 v54, v35, v35
	v_fmac_f32_e32 v53, v36, v36
	v_fmac_f32_e32 v54, v34, v34
	v_add_f32_e32 v36, v36, v37
	v_add_f32_e32 v34, v34, v35
	v_add_f32_e32 v35, v38, v39
	v_add_f32_e32 v37, v40, v41
	v_add_f32_e32 v35, v35, v37
	v_add_f32_e32 v44, v44, v45
	v_add_f32_e32 v42, v42, v43
	v_add_f32_e32 v43, v46, v47
	v_add_f32_e32 v45, v48, v49
	v_add_f32_e32 v34, v35, v34
	v_add_f32_e32 v43, v43, v45
	v_add_f32_e32 v34, v36, v34
	v_and_b32_e32 v36, 64, v183
	v_add_f32_e32 v42, v43, v42
	v_xor_b32_e32 v35, 16, v183
	v_add_u32_e32 v36, 64, v36
	v_mul_f32_e32 v55, v39, v39
	v_mul_f32_e32 v56, v41, v41
	v_add_f32_e32 v42, v44, v42
	v_cmp_lt_i32_e32 vcc, v35, v36
	v_fmac_f32_e32 v55, v38, v38
	v_fmac_f32_e32 v56, v40, v40
	v_add_f32_e32 v42, 0, v42
	v_cndmask_b32_e32 v35, v183, v35, vcc
	v_add_f32_e32 v34, v42, v34
	v_lshlrev_b32_e32 v35, 2, v35
	v_add_f32_e32 v38, v55, v56
	ds_bpermute_b32 v37, v35, v34
	v_add_f32_e32 v38, v38, v54
	v_add_f32_e32 v38, v53, v38
	v_add_f32_e32 v38, v52, v38
	ds_bpermute_b32 v39, v35, v38
	s_waitcnt lgkmcnt(0)
	v_add_f32_e32 v34, v34, v37
	v_xor_b32_e32 v37, 32, v183
	v_cmp_lt_i32_e32 vcc, v37, v36
	v_add_f32_e32 v36, v38, v39
	s_nop 0
	v_cndmask_b32_e32 v35, v183, v37, vcc
	v_lshlrev_b32_e32 v37, 2, v35
	ds_bpermute_b32 v35, v37, v34
	ds_bpermute_b32 v37, v37, v36
	s_and_saveexec_b64 s[8:9], s[2:3]
	s_cbranch_execz .LBB0_237
	v_lshlrev_b64 v[38:39], 2, v[50:51]
	v_lshl_add_u64 v[40:41], s[78:79], 0, v[38:39]
	v_lshl_add_u64 v[38:39], s[76:77], 0, v[38:39]
	s_waitcnt lgkmcnt(0)
	v_add_f32_e32 v34, v34, v35
	v_add_f32_e32 v36, v36, v37
	global_atomic_add_f32 v[38:39], v34, off
	global_atomic_add_f32 v[40:41], v36, off

; __device__ __forceinline__ unsigned cvt_pk_bf16(float lo, float hi) { unsigned r; asm volatile("v_cvt_pk_bf16_f32 %0, %1, %2" : "=v"(r) : "v"(lo), "v"(hi)); return r; }
; __device__ __forceinline__ float gelu_t(float x) { const float u = 0.7978845608028654f * (x + 0.044715f * x * x * x); return x * fast_rcp(1.0f + fast_exp2(-2.8853900817779268f * u)); }
;     __device__ __forceinline__ void operator()(const f32x4 (&acc)[2][2][4][2], const Unit& u, int wr, int wc, int fr, int fq) const {
;     ...
;                 for (int m = 0; m < 4; ++m) { const int row = row0 + ai * HALF + m * 16; bf16_t* rowp = dst + (size_t)row * 512 + col0; float s1 = 0.f, s2 = 0.f;
; #pragma unroll
;                     for (int bj = 0; bj < 2; ++bj) { f32x4 v0 = acc[ai][bj][m][0], v1 = acc[ai][bj][m][1];
; #pragma unroll
;                         for (int j = 0; j < 4; ++j) { v0[j] = gelu_t(v0[j]); v1[j] = gelu_t(v1[j]); }
;                         s1 += (v0[0] + v0[1]) + (v0[2] + v0[3]) + (v1[0] + v1[1]) + (v1[2] + v1[3]);
;                         s2 += (v0[0] * v0[0] + v0[1] * v0[1]) + (v0[2] * v0[2] + v0[3] * v0[3]) + (v1[0] * v1[0] + v1[1] * v1[1]) + (v1[2] * v1[2] + v1[3] * v1[3]);
;                         u32x4 w; w.x = cvt_pk_bf16(v0[0], v0[1]); w.y = cvt_pk_bf16(v0[2], v0[3]); w.z = cvt_pk_bf16(v1[0], v1[1]); w.w = cvt_pk_bf16(v1[2], v1[3]);
;                         *(u32x4*)(rowp + bj * HALF) = w; }
.LBB0_238:
	v_mul_f32_e32 v38, 0x3d372713, v30
	v_mul_f32_e32 v38, v30, v38
	v_fma_f32 v38, v30, v38, v30
	v_mul_f32_e32 v38, 0x3f4c422a, v38
	v_mul_f32_e32 v38, 0xc038aa3b, v38
	v_exp_f32_e32 v38, v38
	v_add_u32_e32 v34, 0xa0, v166
	s_waitcnt lgkmcnt(0)
	v_ashrrev_i32_e32 v35, 31, v34
	v_lshlrev_b64 v[36:37], 10, v[34:35]
	v_add_f32_e32 v38, 1.0, v38
	v_rcp_f32_e32 v38, v38
	v_lshl_add_u64 v[36:37], v[130:131], 0, v[36:37]
	s_and_b64 vcc, exec, s[6:7]
	v_mul_f32_e32 v30, v30, v38
	v_mul_f32_e32 v38, 0x3d372713, v26
	v_mul_f32_e32 v38, v26, v38
	v_fma_f32 v38, v26, v38, v26
	v_mul_f32_e32 v38, 0x3f4c422a, v38
	v_mul_f32_e32 v38, 0xc038aa3b, v38
	v_exp_f32_e32 v38, v38
	s_nop 0
	v_add_f32_e32 v38, 1.0, v38
	v_rcp_f32_e32 v38, v38
	s_nop 0
	v_mul_f32_e32 v26, v26, v38
	v_mul_f32_e32 v38, 0x3d372713, v31
	v_mul_f32_e32 v38, v31, v38
	v_fma_f32 v38, v31, v38, v31
	v_mul_f32_e32 v38, 0x3f4c422a, v38
	v_mul_f32_e32 v38, 0xc038aa3b, v38
	v_exp_f32_e32 v38, v38
	s_nop 0
	v_add_f32_e32 v38, 1.0, v38
	v_rcp_f32_e32 v38, v38
	s_nop 0
	v_mul_f32_e32 v31, v31, v38
	v_mul_f32_e32 v38, 0x3d372713, v27
	v_mul_f32_e32 v38, v27, v38
	v_fma_f32 v38, v27, v38, v27
	v_mul_f32_e32 v38, 0x3f4c422a, v38
	v_mul_f32_e32 v38, 0xc038aa3b, v38
	v_exp_f32_e32 v38, v38
	s_nop 0
	v_add_f32_e32 v38, 1.0, v38
	v_rcp_f32_e32 v38, v38
	s_nop 0
	v_mul_f32_e32 v27, v27, v38
	v_mul_f32_e32 v38, 0x3d372713, v32
	v_mul_f32_e32 v38, v32, v38
	v_fma_f32 v38, v32, v38, v32
	v_mul_f32_e32 v38, 0x3f4c422a, v38
	v_mul_f32_e32 v38, 0xc038aa3b, v38
	v_exp_f32_e32 v38, v38
	s_nop 0
	v_add_f32_e32 v38, 1.0, v38
	v_rcp_f32_e32 v38, v38
	s_nop 0
	v_mul_f32_e32 v32, v32, v38
	v_mul_f32_e32 v38, 0x3d372713, v28
	v_mul_f32_e32 v38, v28, v38
	v_fma_f32 v38, v28, v38, v28
	v_mul_f32_e32 v38, 0x3f4c422a, v38
	v_mul_f32_e32 v38, 0xc038aa3b, v38
	v_exp_f32_e32 v38, v38
	s_nop 0
	v_add_f32_e32 v38, 1.0, v38
	v_rcp_f32_e32 v38, v38
	s_nop 0
	v_mul_f32_e32 v28, v28, v38
	v_mul_f32_e32 v38, 0x3d372713, v33
	v_mul_f32_e32 v38, v33, v38
	v_fma_f32 v38, v33, v38, v33
	v_mul_f32_e32 v38, 0x3f4c422a, v38
	v_mul_f32_e32 v38, 0xc038aa3b, v38
	v_exp_f32_e32 v38, v38
	s_nop 0
	v_add_f32_e32 v38, 1.0, v38
	v_rcp_f32_e32 v38, v38
	s_nop 0
	v_mul_f32_e32 v33, v33, v38
	v_mul_f32_e32 v38, 0x3d372713, v29
	v_mul_f32_e32 v38, v29, v38
	v_fma_f32 v38, v29, v38, v29
	v_mul_f32_e32 v38, 0x3f4c422a, v38
	v_mul_f32_e32 v38, 0xc038aa3b, v38
	v_exp_f32_e32 v38, v38
	s_nop 0
	v_add_f32_e32 v38, 1.0, v38
	v_rcp_f32_e32 v38, v38
	s_nop 0
	v_mul_f32_e32 v29, v29, v38
	v_cvt_pk_bf16_f32 v38, v30, v31
	v_cvt_pk_bf16_f32 v39, v32, v33
	v_cvt_pk_bf16_f32 v40, v26, v27
	v_cvt_pk_bf16_f32 v41, v28, v29
	s_waitcnt lgkmcnt(0)
	global_store_dwordx4 v224, v[230:233], s[98:99] offset:256
	s_nop 0
	v_readfirstlane_b32 s98, v36
	v_readfirstlane_b32 s99, v37
	ds_write_b128 v222, v[38:41]
	ds_read_b128 v[230:233], v223
	s_nop 1
	v_mul_f32_e32 v38, 0x3d372713, v22
	v_mul_f32_e32 v38, v22, v38
	v_fma_f32 v38, v22, v38, v22
	v_mul_f32_e32 v38, 0x3f4c422a, v38
	v_mul_f32_e32 v38, 0xc038aa3b, v38
	v_exp_f32_e32 v38, v38
	s_nop 0
	v_add_f32_e32 v38, 1.0, v38
	v_rcp_f32_e32 v38, v38
	s_nop 0
	v_mul_f32_e32 v22, v22, v38
	v_mul_f32_e32 v38, 0x3d372713, v18
	v_mul_f32_e32 v38, v18, v38
	v_fma_f32 v38, v18, v38, v18
	v_mul_f32_e32 v38, 0x3f4c422a, v38
	v_mul_f32_e32 v38, 0xc038aa3b, v38
	v_exp_f32_e32 v38, v38
	s_nop 0
	v_add_f32_e32 v38, 1.0, v38
	v_rcp_f32_e32 v38, v38
	s_nop 0
	v_mul_f32_e32 v18, v18, v38
	v_mul_f32_e32 v38, 0x3d372713, v23
	v_mul_f32_e32 v38, v23, v38
	v_fma_f32 v38, v23, v38, v23
	v_mul_f32_e32 v38, 0x3f4c422a, v38
	v_mul_f32_e32 v38, 0xc038aa3b, v38
	v_exp_f32_e32 v38, v38
	s_nop 0
	v_add_f32_e32 v38, 1.0, v38
	v_rcp_f32_e32 v38, v38
	s_nop 0
	v_mul_f32_e32 v23, v23, v38
	v_mul_f32_e32 v38, 0x3d372713, v19
	v_mul_f32_e32 v38, v19, v38
	v_fma_f32 v38, v19, v38, v19
	v_mul_f32_e32 v38, 0x3f4c422a, v38
	v_mul_f32_e32 v38, 0xc038aa3b, v38
	v_exp_f32_e32 v38, v38
	s_nop 0
	v_add_f32_e32 v38, 1.0, v38
	v_rcp_f32_e32 v38, v38
	s_nop 0
	v_mul_f32_e32 v19, v19, v38
	v_mul_f32_e32 v38, 0x3d372713, v24
	v_mul_f32_e32 v38, v24, v38
	v_fma_f32 v38, v24, v38, v24
	v_mul_f32_e32 v38, 0x3f4c422a, v38
	v_mul_f32_e32 v38, 0xc038aa3b, v38
	v_exp_f32_e32 v38, v38
	s_nop 0
	v_add_f32_e32 v38, 1.0, v38
	v_rcp_f32_e32 v38, v38
	s_nop 0
	v_mul_f32_e32 v24, v24, v38
	v_mul_f32_e32 v38, 0x3d372713, v20
	v_mul_f32_e32 v38, v20, v38
	v_fma_f32 v38, v20, v38, v20
	v_mul_f32_e32 v38, 0x3f4c422a, v38
	v_mul_f32_e32 v38, 0xc038aa3b, v38
	v_exp_f32_e32 v38, v38
	s_nop 0
	v_add_f32_e32 v38, 1.0, v38
	v_rcp_f32_e32 v38, v38
	s_nop 0
	v_mul_f32_e32 v20, v20, v38
	v_mul_f32_e32 v38, 0x3d372713, v25
	v_mul_f32_e32 v38, v25, v38
	v_fma_f32 v38, v25, v38, v25
	v_mul_f32_e32 v38, 0x3f4c422a, v38
	v_mul_f32_e32 v38, 0xc038aa3b, v38
	v_exp_f32_e32 v38, v38
	s_nop 0
	v_add_f32_e32 v38, 1.0, v38
	v_rcp_f32_e32 v38, v38
	s_nop 0
	v_mul_f32_e32 v25, v25, v38
	v_mul_f32_e32 v38, 0x3d372713, v21
	v_mul_f32_e32 v38, v21, v38
	v_fma_f32 v38, v21, v38, v21
	v_mul_f32_e32 v38, 0x3f4c422a, v38
	v_mul_f32_e32 v38, 0xc038aa3b, v38
	v_exp_f32_e32 v38, v38
	s_nop 0
	v_add_f32_e32 v38, 1.0, v38
	v_rcp_f32_e32 v38, v38
	s_nop 0
	v_mul_f32_e32 v21, v21, v38
	v_cvt_pk_bf16_f32 v38, v22, v23
	v_cvt_pk_bf16_f32 v39, v24, v25
	v_cvt_pk_bf16_f32 v40, v18, v19
	v_cvt_pk_bf16_f32 v41, v20, v21
	s_waitcnt lgkmcnt(0)
	global_store_dwordx4 v224, v[230:233], s[98:99]
	s_nop 0
	v_readfirstlane_b32 s98, v36
	v_readfirstlane_b32 s99, v37
	ds_write_b128 v222, v[38:41]
	ds_read_b128 v[230:233], v223
	s_cbranch_vccnz .LBB0_242
; __device__ __forceinline__ unsigned cvt_pk_bf16(float lo, float hi) { unsigned r; asm volatile("v_cvt_pk_bf16_f32 %0, %1, %2" : "=v"(r) : "v"(lo), "v"(hi)); return r; }
; __device__ __forceinline__ float quad_sum(float s) { s += __shfl_xor(s, 16); s += __shfl_xor(s, 32); return s; }
;     __device__ __forceinline__ void operator()(const f32x4 (&acc)[2][2][4][2], const Unit& u, int wr, int wc, int fr, int fq) const {
;     ...
;                         s1 += (v0[0] + v0[1]) + (v0[2] + v0[3]) + (v1[0] + v1[1]) + (v1[2] + v1[3]);
;                         s2 += (v0[0] * v0[0] + v0[1] * v0[1]) + (v0[2] * v0[2] + v0[3] * v0[3]) + (v1[0] * v1[0] + v1[1] * v1[1]) + (v1[2] * v1[2] + v1[3] * v1[3]);
;                         u32x4 w; w.x = cvt_pk_bf16(v0[0], v0[1]); w.y = cvt_pk_bf16(v0[2], v0[3]); w.z = cvt_pk_bf16(v1[0], v1[1]); w.w = cvt_pk_bf16(v1[2], v1[3]);
;                         *(u32x4*)(rowp + bj * HALF) = w; }
;                     if (stats) { s1 = quad_sum(s1); s2 = quad_sum(s2); if (fq == 0) { atomicAdd(st1 + row, s1); atomicAdd(st2 + row, s2); } } }
	s_nop 0
	v_mul_f32_e32 v38, v31, v31
	v_mul_f32_e32 v39, v33, v33
	v_mul_f32_e32 v37, v27, v27
	v_fmac_f32_e32 v38, v30, v30
	v_fmac_f32_e32 v39, v32, v32
	v_mul_f32_e32 v36, v29, v29
	v_fmac_f32_e32 v37, v26, v26
	v_add_f32_e32 v38, v38, v39
	v_fmac_f32_e32 v36, v28, v28
	v_add_f32_e32 v37, v38, v37
	v_add_f32_e32 v36, v36, v37
	v_mul_f32_e32 v37, v21, v21
	v_mul_f32_e32 v38, v19, v19
	v_fmac_f32_e32 v37, v20, v20
	v_fmac_f32_e32 v38, v18, v18
	v_add_f32_e32 v20, v20, v21
	v_add_f32_e32 v18, v18, v19
	v_add_f32_e32 v19, v22, v23
	v_add_f32_e32 v21, v24, v25
	v_add_f32_e32 v19, v19, v21
	v_add_f32_e32 v28, v28, v29
	v_add_f32_e32 v26, v26, v27
	v_add_f32_e32 v27, v30, v31
	v_add_f32_e32 v29, v32, v33
	v_add_f32_e32 v18, v19, v18
	v_add_f32_e32 v27, v27, v29
	v_add_f32_e32 v18, v20, v18
	v_and_b32_e32 v20, 64, v183
	v_add_f32_e32 v26, v27, v26
	v_xor_b32_e32 v19, 16, v183
	v_add_u32_e32 v20, 64, v20
	v_mul_f32_e32 v39, v23, v23
	v_mul_f32_e32 v40, v25, v25
	v_add_f32_e32 v26, v28, v26
	v_cmp_lt_i32_e32 vcc, v19, v20
	v_fmac_f32_e32 v39, v22, v22
	v_fmac_f32_e32 v40, v24, v24
	v_add_f32_e32 v26, 0, v26
	v_cndmask_b32_e32 v19, v183, v19, vcc
	v_add_f32_e32 v18, v26, v18
	v_lshlrev_b32_e32 v19, 2, v19
	v_add_f32_e32 v22, v39, v40
	ds_bpermute_b32 v21, v19, v18
	v_add_f32_e32 v22, v22, v38
	v_add_f32_e32 v22, v37, v22
	v_add_f32_e32 v22, v36, v22
	ds_bpermute_b32 v23, v19, v22
	s_waitcnt lgkmcnt(0)
	v_add_f32_e32 v18, v18, v21
	v_xor_b32_e32 v21, 32, v183
	v_cmp_lt_i32_e32 vcc, v21, v20
	v_add_f32_e32 v20, v22, v23
	s_nop 0
	v_cndmask_b32_e32 v19, v183, v21, vcc
	v_lshlrev_b32_e32 v21, 2, v19
	ds_bpermute_b32 v19, v21, v18
	ds_bpermute_b32 v21, v21, v20
	s_and_saveexec_b64 s[8:9], s[2:3]
	s_cbranch_execz .LBB0_241
	v_lshlrev_b64 v[22:23], 2, v[34:35]
	v_lshl_add_u64 v[24:25], s[78:79], 0, v[22:23]
	v_lshl_add_u64 v[22:23], s[76:77], 0, v[22:23]
	s_waitcnt lgkmcnt(0)
	v_add_f32_e32 v18, v18, v19
	v_add_f32_e32 v20, v20, v21
	global_atomic_add_f32 v[22:23], v18, off
	global_atomic_add_f32 v[24:25], v20, off

; __device__ __forceinline__ unsigned cvt_pk_bf16(float lo, float hi) { unsigned r; asm volatile("v_cvt_pk_bf16_f32 %0, %1, %2" : "=v"(r) : "v"(lo), "v"(hi)); return r; }
; __device__ __forceinline__ float gelu_t(float x) { const float u = 0.7978845608028654f * (x + 0.044715f * x * x * x); return x * fast_rcp(1.0f + fast_exp2(-2.8853900817779268f * u)); }
;     __device__ __forceinline__ void operator()(const f32x4 (&acc)[2][2][4][2], const Unit& u, int wr, int wc, int fr, int fq) const {
;     ...
;                 for (int m = 0; m < 4; ++m) { const int row = row0 + ai * HALF + m * 16; bf16_t* rowp = dst + (size_t)row * 512 + col0; float s1 = 0.f, s2 = 0.f;
; #pragma unroll
;                     for (int bj = 0; bj < 2; ++bj) { f32x4 v0 = acc[ai][bj][m][0], v1 = acc[ai][bj][m][1];
; #pragma unroll
;                         for (int j = 0; j < 4; ++j) { v0[j] = gelu_t(v0[j]); v1[j] = gelu_t(v1[j]); }
;                         s1 += (v0[0] + v0[1]) + (v0[2] + v0[3]) + (v1[0] + v1[1]) + (v1[2] + v1[3]);
;                         s2 += (v0[0] * v0[0] + v0[1] * v0[1]) + (v0[2] * v0[2] + v0[3] * v0[3]) + (v1[0] * v1[0] + v1[1] * v1[1]) + (v1[2] * v1[2] + v1[3] * v1[3]);
;                         u32x4 w; w.x = cvt_pk_bf16(v0[0], v0[1]); w.y = cvt_pk_bf16(v0[2], v0[3]); w.z = cvt_pk_bf16(v1[0], v1[1]); w.w = cvt_pk_bf16(v1[2], v1[3]);
;                         *(u32x4*)(rowp + bj * HALF) = w; }
.LBB0_242:
	v_mul_f32_e32 v22, 0x3d372713, v14
	v_mul_f32_e32 v22, v14, v22
	v_fma_f32 v22, v14, v22, v14
	v_mul_f32_e32 v22, 0x3f4c422a, v22
	v_mul_f32_e32 v22, 0xc038aa3b, v22
	v_exp_f32_e32 v22, v22
	v_add_u32_e32 v18, 0xb0, v166
	s_waitcnt lgkmcnt(0)
	v_ashrrev_i32_e32 v19, 31, v18
	v_lshlrev_b64 v[20:21], 10, v[18:19]
	v_add_f32_e32 v22, 1.0, v22
	v_rcp_f32_e32 v22, v22
	v_lshl_add_u64 v[20:21], v[130:131], 0, v[20:21]
	s_and_b64 vcc, exec, s[6:7]
	v_mul_f32_e32 v14, v14, v22
	v_mul_f32_e32 v22, 0x3d372713, v10
	v_mul_f32_e32 v22, v10, v22
	v_fma_f32 v22, v10, v22, v10
	v_mul_f32_e32 v22, 0x3f4c422a, v22
	v_mul_f32_e32 v22, 0xc038aa3b, v22
	v_exp_f32_e32 v22, v22
	s_nop 0
	v_add_f32_e32 v22, 1.0, v22
	v_rcp_f32_e32 v22, v22
	s_nop 0
	v_mul_f32_e32 v10, v10, v22
	v_mul_f32_e32 v22, 0x3d372713, v15
	v_mul_f32_e32 v22, v15, v22
	v_fma_f32 v22, v15, v22, v15
	v_mul_f32_e32 v22, 0x3f4c422a, v22
	v_mul_f32_e32 v22, 0xc038aa3b, v22
	v_exp_f32_e32 v22, v22
	s_nop 0
	v_add_f32_e32 v22, 1.0, v22
	v_rcp_f32_e32 v22, v22
	s_nop 0
	v_mul_f32_e32 v15, v15, v22
	v_mul_f32_e32 v22, 0x3d372713, v11
	v_mul_f32_e32 v22, v11, v22
	v_fma_f32 v22, v11, v22, v11
	v_mul_f32_e32 v22, 0x3f4c422a, v22
	v_mul_f32_e32 v22, 0xc038aa3b, v22
	v_exp_f32_e32 v22, v22
	s_nop 0
	v_add_f32_e32 v22, 1.0, v22
	v_rcp_f32_e32 v22, v22
	s_nop 0
	v_mul_f32_e32 v11, v11, v22
	v_mul_f32_e32 v22, 0x3d372713, v16
	v_mul_f32_e32 v22, v16, v22
	v_fma_f32 v22, v16, v22, v16
	v_mul_f32_e32 v22, 0x3f4c422a, v22
	v_mul_f32_e32 v22, 0xc038aa3b, v22
	v_exp_f32_e32 v22, v22
	s_nop 0
	v_add_f32_e32 v22, 1.0, v22
	v_rcp_f32_e32 v22, v22
	s_nop 0
	v_mul_f32_e32 v16, v16, v22
	v_mul_f32_e32 v22, 0x3d372713, v12
	v_mul_f32_e32 v22, v12, v22
	v_fma_f32 v22, v12, v22, v12
	v_mul_f32_e32 v22, 0x3f4c422a, v22
	v_mul_f32_e32 v22, 0xc038aa3b, v22
	v_exp_f32_e32 v22, v22
	s_nop 0
	v_add_f32_e32 v22, 1.0, v22
	v_rcp_f32_e32 v22, v22
	s_nop 0
	v_mul_f32_e32 v12, v12, v22
	v_mul_f32_e32 v22, 0x3d372713, v17
	v_mul_f32_e32 v22, v17, v22
	v_fma_f32 v22, v17, v22, v17
	v_mul_f32_e32 v22, 0x3f4c422a, v22
	v_mul_f32_e32 v22, 0xc038aa3b, v22
	v_exp_f32_e32 v22, v22
	s_nop 0
	v_add_f32_e32 v22, 1.0, v22
	v_rcp_f32_e32 v22, v22
	s_nop 0
	v_mul_f32_e32 v17, v17, v22
	v_mul_f32_e32 v22, 0x3d372713, v13
	v_mul_f32_e32 v22, v13, v22
	v_fma_f32 v22, v13, v22, v13
	v_mul_f32_e32 v22, 0x3f4c422a, v22
	v_mul_f32_e32 v22, 0xc038aa3b, v22
	v_exp_f32_e32 v22, v22
	s_nop 0
	v_add_f32_e32 v22, 1.0, v22
	v_rcp_f32_e32 v22, v22
	s_nop 0
	v_mul_f32_e32 v13, v13, v22
	v_cvt_pk_bf16_f32 v22, v14, v15
	v_cvt_pk_bf16_f32 v23, v16, v17
	v_cvt_pk_bf16_f32 v24, v10, v11
	v_cvt_pk_bf16_f32 v25, v12, v13
	s_waitcnt lgkmcnt(0)
	global_store_dwordx4 v224, v[230:233], s[98:99] offset:256
	s_nop 0
	v_readfirstlane_b32 s98, v20
	v_readfirstlane_b32 s99, v21
	ds_write_b128 v222, v[22:25]
	ds_read_b128 v[230:233], v223
	s_nop 1
	v_mul_f32_e32 v22, 0x3d372713, v6
	v_mul_f32_e32 v22, v6, v22
	v_fma_f32 v22, v6, v22, v6
	v_mul_f32_e32 v22, 0x3f4c422a, v22
	v_mul_f32_e32 v22, 0xc038aa3b, v22
	v_exp_f32_e32 v22, v22
	s_nop 0
	v_add_f32_e32 v22, 1.0, v22
	v_rcp_f32_e32 v22, v22
	s_nop 0
	v_mul_f32_e32 v6, v6, v22
	v_mul_f32_e32 v22, 0x3d372713, v2
	v_mul_f32_e32 v22, v2, v22
	v_fma_f32 v22, v2, v22, v2
	v_mul_f32_e32 v22, 0x3f4c422a, v22
	v_mul_f32_e32 v22, 0xc038aa3b, v22
	v_exp_f32_e32 v22, v22
	s_nop 0
	v_add_f32_e32 v22, 1.0, v22
	v_rcp_f32_e32 v22, v22
	s_nop 0
	v_mul_f32_e32 v2, v2, v22
	v_mul_f32_e32 v22, 0x3d372713, v7
	v_mul_f32_e32 v22, v7, v22
	v_fma_f32 v22, v7, v22, v7
	v_mul_f32_e32 v22, 0x3f4c422a, v22
	v_mul_f32_e32 v22, 0xc038aa3b, v22
	v_exp_f32_e32 v22, v22
	s_nop 0
	v_add_f32_e32 v22, 1.0, v22
	v_rcp_f32_e32 v22, v22
	s_nop 0
	v_mul_f32_e32 v7, v7, v22
	v_mul_f32_e32 v22, 0x3d372713, v3
	v_mul_f32_e32 v22, v3, v22
	v_fma_f32 v22, v3, v22, v3
	v_mul_f32_e32 v22, 0x3f4c422a, v22
	v_mul_f32_e32 v22, 0xc038aa3b, v22
	v_exp_f32_e32 v22, v22
	s_nop 0
	v_add_f32_e32 v22, 1.0, v22
	v_rcp_f32_e32 v22, v22
	s_nop 0
	v_mul_f32_e32 v3, v3, v22
	v_mul_f32_e32 v22, 0x3d372713, v8
	v_mul_f32_e32 v22, v8, v22
	v_fma_f32 v22, v8, v22, v8
	v_mul_f32_e32 v22, 0x3f4c422a, v22
	v_mul_f32_e32 v22, 0xc038aa3b, v22
	v_exp_f32_e32 v22, v22
	s_nop 0
	v_add_f32_e32 v22, 1.0, v22
	v_rcp_f32_e32 v22, v22
	s_nop 0
	v_mul_f32_e32 v8, v8, v22
	v_mul_f32_e32 v22, 0x3d372713, v4
	v_mul_f32_e32 v22, v4, v22
	v_fma_f32 v22, v4, v22, v4
	v_mul_f32_e32 v22, 0x3f4c422a, v22
	v_mul_f32_e32 v22, 0xc038aa3b, v22
	v_exp_f32_e32 v22, v22
	s_nop 0
	v_add_f32_e32 v22, 1.0, v22
	v_rcp_f32_e32 v22, v22
	s_nop 0
	v_mul_f32_e32 v4, v4, v22
	v_mul_f32_e32 v22, 0x3d372713, v9
	v_mul_f32_e32 v22, v9, v22
	v_fma_f32 v22, v9, v22, v9
	v_mul_f32_e32 v22, 0x3f4c422a, v22
	v_mul_f32_e32 v22, 0xc038aa3b, v22
	v_exp_f32_e32 v22, v22
	s_nop 0
	v_add_f32_e32 v22, 1.0, v22
	v_rcp_f32_e32 v22, v22
	s_nop 0
	v_mul_f32_e32 v9, v9, v22
	v_mul_f32_e32 v22, 0x3d372713, v5
	v_mul_f32_e32 v22, v5, v22
	v_fma_f32 v22, v5, v22, v5
	v_mul_f32_e32 v22, 0x3f4c422a, v22
	v_mul_f32_e32 v22, 0xc038aa3b, v22
	v_exp_f32_e32 v22, v22
	s_nop 0
	v_add_f32_e32 v22, 1.0, v22
	v_rcp_f32_e32 v22, v22
	s_nop 0
	v_mul_f32_e32 v5, v5, v22
	v_cvt_pk_bf16_f32 v22, v6, v7
	v_cvt_pk_bf16_f32 v23, v8, v9
	v_cvt_pk_bf16_f32 v24, v2, v3
	v_cvt_pk_bf16_f32 v25, v4, v5
	s_waitcnt lgkmcnt(0)
	global_store_dwordx4 v224, v[230:233], s[98:99]
	s_nop 0
	v_readfirstlane_b32 s98, v20
	v_readfirstlane_b32 s99, v21
	ds_write_b128 v222, v[22:25]
	ds_read_b128 v[230:233], v223
	s_nop 1
	s_waitcnt lgkmcnt(0)
	global_store_dwordx4 v224, v[230:233], s[98:99] offset:256
	s_cbranch_vccnz .LBB0_246
; __device__ __forceinline__ unsigned cvt_pk_bf16(float lo, float hi) { unsigned r; asm volatile("v_cvt_pk_bf16_f32 %0, %1, %2" : "=v"(r) : "v"(lo), "v"(hi)); return r; }
; __device__ __forceinline__ float quad_sum(float s) { s += __shfl_xor(s, 16); s += __shfl_xor(s, 32); return s; }
;     __device__ __forceinline__ void operator()(const f32x4 (&acc)[2][2][4][2], const Unit& u, int wr, int wc, int fr, int fq) const {
;     ...
;                         s1 += (v0[0] + v0[1]) + (v0[2] + v0[3]) + (v1[0] + v1[1]) + (v1[2] + v1[3]);
;                         s2 += (v0[0] * v0[0] + v0[1] * v0[1]) + (v0[2] * v0[2] + v0[3] * v0[3]) + (v1[0] * v1[0] + v1[1] * v1[1]) + (v1[2] * v1[2] + v1[3] * v1[3]);
;                         u32x4 w; w.x = cvt_pk_bf16(v0[0], v0[1]); w.y = cvt_pk_bf16(v0[2], v0[3]); w.z = cvt_pk_bf16(v1[0], v1[1]); w.w = cvt_pk_bf16(v1[2], v1[3]);
;                         *(u32x4*)(rowp + bj * HALF) = w; }
;                     if (stats) { s1 = quad_sum(s1); s2 = quad_sum(s2); if (fq == 0) { atomicAdd(st1 + row, s1); atomicAdd(st2 + row, s2); } } }
	s_nop 0
	v_mul_f32_e32 v22, v15, v15
	v_mul_f32_e32 v23, v17, v17
	v_mul_f32_e32 v21, v11, v11
	v_fmac_f32_e32 v22, v14, v14
	v_fmac_f32_e32 v23, v16, v16
	v_mul_f32_e32 v20, v13, v13
	v_fmac_f32_e32 v21, v10, v10
	v_add_f32_e32 v22, v22, v23
	v_fmac_f32_e32 v20, v12, v12
	v_add_f32_e32 v21, v22, v21
	v_add_f32_e32 v20, v20, v21
	v_mul_f32_e32 v21, v5, v5
	v_mul_f32_e32 v22, v3, v3
	v_fmac_f32_e32 v21, v4, v4
	v_fmac_f32_e32 v22, v2, v2
	v_add_f32_e32 v4, v4, v5
	v_add_f32_e32 v2, v2, v3
	v_add_f32_e32 v3, v6, v7
	v_add_f32_e32 v5, v8, v9
	v_add_f32_e32 v3, v3, v5
	v_add_f32_e32 v12, v12, v13
	v_add_f32_e32 v10, v10, v11
	v_add_f32_e32 v11, v14, v15
	v_add_f32_e32 v13, v16, v17
	v_add_f32_e32 v2, v3, v2
	v_add_f32_e32 v11, v11, v13
	v_add_f32_e32 v2, v4, v2
	v_and_b32_e32 v4, 64, v183
	v_add_f32_e32 v10, v11, v10
	v_xor_b32_e32 v3, 16, v183
	v_add_u32_e32 v4, 64, v4
	v_mul_f32_e32 v23, v7, v7
	v_mul_f32_e32 v24, v9, v9
	v_add_f32_e32 v10, v12, v10
	v_cmp_lt_i32_e32 vcc, v3, v4
	v_fmac_f32_e32 v23, v6, v6
	v_fmac_f32_e32 v24, v8, v8
	v_add_f32_e32 v10, 0, v10
	v_cndmask_b32_e32 v3, v183, v3, vcc
	v_add_f32_e32 v2, v10, v2
	v_lshlrev_b32_e32 v3, 2, v3
	v_add_f32_e32 v6, v23, v24
	ds_bpermute_b32 v5, v3, v2
	v_add_f32_e32 v6, v6, v22
	v_add_f32_e32 v6, v21, v6
	v_add_f32_e32 v6, v20, v6
	ds_bpermute_b32 v7, v3, v6
	s_waitcnt lgkmcnt(0)
	v_add_f32_e32 v2, v2, v5
	v_xor_b32_e32 v5, 32, v183
	v_cmp_lt_i32_e32 vcc, v5, v4
	v_add_f32_e32 v4, v6, v7
	s_nop 0
	v_cndmask_b32_e32 v3, v183, v5, vcc
	v_lshlrev_b32_e32 v5, 2, v3
	ds_bpermute_b32 v3, v5, v2
	ds_bpermute_b32 v5, v5, v4
	s_and_saveexec_b64 s[6:7], s[2:3]
	s_cbranch_execz .LBB0_245
	v_lshlrev_b64 v[6:7], 2, v[18:19]
	v_lshl_add_u64 v[8:9], s[78:79], 0, v[6:7]
	v_lshl_add_u64 v[6:7], s[76:77], 0, v[6:7]
	s_waitcnt lgkmcnt(0)
	v_add_f32_e32 v2, v2, v3
	v_add_f32_e32 v4, v4, v5
	global_atomic_add_f32 v[6:7], v2, off
	global_atomic_add_f32 v[8:9], v4, off
